# v17: MLA loop back-edge rotation - per-iteration address/scalar setup moved from loop head to tail before the barrier (on v14)
# speedup vs baseline: 1.0044x; 1.0044x over previous
; DI int my_tid() { int t = threadIdx.x; asm volatile("" : "+v"(t)); return t; }
; DI float bf_lo(unsigned u) { return __uint_as_float(u << 16); }
; DI float bf_hi(unsigned u) { return __uint_as_float(u & 0xffff0000u); }
; DI float rsqrt_f(float x) { return __builtin_amdgcn_rsqf(x); }
; DI void rope_cs(int pos, int i, float& c, float& s) {
;   double t = (double)pos * ROPE_TURNS[i];
;   t -= floor(t);
;   float fr = (float)t;
;   s = __builtin_amdgcn_sinf(fr);
;   c = __builtin_amdgcn_cosf(fr);
; }
; DI void mla_item(PRef p, int j, int seq, int head, int qb, char* smem) {
;   const int tid = my_tid(), lane = tid & 63, w = tid >> 6, r = lane & 31, h = lane >> 5;
;   const int s0 = seq == 0 ? 0 : TP + (seq - 1) * SS;
;   const int S = seq == 0 ? TP : SS;
;   const int pos = qb * 256 + w * 32 + r;
;   const int tok = s0 + pos;
;   const short* Q = (const short*)(p.ws + OFF_Q);
;   const float* gq = p.in[10] + j * 96;
;   float qv[6][8];
;   float ss = 0.f;
; #pragma unroll
;   for (int ks = 0; ks < 6; ks++) {
;     u32x4 t = *(const u32x4*)(Q + (size_t)tok * 1152 + head * 96 + ks * 16 + 8 * h);
; #pragma unroll
;     for (int e = 0; e < 4; e++) {
;       qv[ks][2 * e] = bf_lo(t[e]);
;       qv[ks][2 * e + 1] = bf_hi(t[e]);
;     }
; #pragma unroll
;     for (int e = 0; e < 8; e++) ss += qv[ks][e] * qv[ks][e];
;   }
;   ss += __shfl_xor(ss, 32);
;   const float f = rsqrt_f(ss * (1.f / 96.f) + EPS);
;   const float sc = 0.10206207261596575f * LOG2E;
; #pragma unroll
;   for (int ks = 0; ks < 6; ks++)
; #pragma unroll
;     for (int e = 0; e < 8; e++) qv[ks][e] *= f * gq[ks * 16 + 8 * h + e];
; #pragma unroll
;   for (int e = 0; e < 8; e++) {
;     float cs, sn;
;     rope_cs(pos, 8 * h + e, cs, sn);
.LBB0_165:
	v_mov_b32_e32 v10, v196
	s_getpc_b64 s[8:9]
	s_add_u32 s8, s8, _ZL10ROPE_TURNS@rel32@lo+4
	s_addc_u32 s9, s9, _ZL10ROPE_TURNS@rel32@hi+12
	v_lshrrev_b32_e32 v0, 2, v10
	v_and_b32_e32 v11, 8, v0
	v_lshlrev_b32_e32 v4, 3, v11
	global_load_dwordx4 v[0:3], v4, s[8:9]
	global_load_dwordx4 v[18:21], v4, s[8:9] offset:16
	global_load_dwordx4 v[22:25], v4, s[8:9] offset:32
	global_load_dwordx4 v[6:9], v4, s[8:9] offset:48
	s_ashr_i32 s8, s20, 2
	s_and_b32 s9, s20, 31
	s_and_b32 s8, s8, -8
	v_readlane_b32 s16, v226, 15
	v_ashrrev_i32_e32 v12, 1, v10
	s_or_b32 s9, s9, s16
	s_or_b32 s8, s8, s52
	v_and_b32_e32 v12, 0xffffffe0, v12
	s_ashr_i32 s16, s8, 1
	v_lshl_add_u32 v12, s9, 8, v12
	v_mov_b64_e32 v[4:5], s[4:5]
	s_mul_i32 s8, s16, 0x60
	v_and_or_b32 v102, v10, 31, v12
	s_movk_i32 s21, 0x900
	s_ashr_i32 s9, s8, 31
	v_mad_i64_i32 v[4:5], s[22:23], v102, s21, v[4:5]
	s_waitcnt vmcnt(11)
	v_lshlrev_b32_e32 v128, 1, v11
	v_lshl_add_u64 v[4:5], s[8:9], 1, v[4:5]
	v_lshl_add_u64 v[4:5], v[4:5], 0, v[128:129]
	global_load_dwordx4 v[44:47], v[4:5], off offset:128
	global_load_dwordx4 v[52:55], v[4:5], off offset:160
	global_load_dwordx4 v[56:59], v[4:5], off offset:64
	global_load_dwordx4 v[60:63], v[4:5], off offset:96
	v_and_b32_e32 v12, 64, v200
	v_xor_b32_e32 v10, 32, v200
	v_add_u32_e32 v12, 64, v12
	v_cmp_lt_i32_e32 vcc, v10, v12
	v_lshlrev_b32_e32 v128, 2, v11
	v_cvt_f64_i32_e32 v[48:49], v102
	v_cndmask_b32_e32 v10, v200, v10, vcc
	v_lshlrev_b32_e32 v103, 2, v10
	global_load_dwordx4 v[10:13], v[4:5], off
	global_load_dwordx4 v[14:17], v[4:5], off offset:32
	s_mul_i32 s8, s16, 0xf00000
	s_mul_hi_i32 s9, s16, 0xf00000
	s_add_u32 s8, s10, s8
	s_addc_u32 s9, s11, s9
	s_mul_i32 s28, s16, 0xa00000
	s_mul_hi_i32 s29, s16, 0xa00000
	s_add_u32 s28, s12, s28
	s_addc_u32 s29, s13, s29
	s_mov_b32 s37, 0x500000
	s_mov_b32 s30, 0x3e16c740
	s_mov_b32 s23, 2
	s_mov_b32 s22, 1
	s_mov_b32 s21, 0
	s_waitcnt vmcnt(9)
	v_mul_f64 v[4:5], v[0:1], v[48:49]
	v_mul_f64 v[26:27], v[2:3], v[48:49]
	s_waitcnt vmcnt(8)
	v_mul_f64 v[28:29], v[18:19], v[48:49]
	v_mul_f64 v[30:31], v[20:21], v[48:49]
	s_waitcnt vmcnt(7)
	v_mul_f64 v[32:33], v[22:23], v[48:49]
	v_mul_f64 v[34:35], v[24:25], v[48:49]
	s_waitcnt vmcnt(6)
	v_mul_f64 v[36:37], v[6:7], v[48:49]
	v_floor_f64_e32 v[4:5], v[4:5]
	v_floor_f64_e32 v[26:27], v[26:27]
	v_floor_f64_e32 v[28:29], v[28:29]
	v_floor_f64_e32 v[30:31], v[30:31]
	v_floor_f64_e32 v[32:33], v[32:33]
	v_floor_f64_e32 v[34:35], v[34:35]
	v_floor_f64_e32 v[36:37], v[36:37]
	v_fma_f64 v[0:1], v[0:1], v[48:49], -v[4:5]
	v_fma_f64 v[2:3], v[2:3], v[48:49], -v[26:27]
	v_fma_f64 v[4:5], v[18:19], v[48:49], -v[28:29]
	v_fma_f64 v[18:19], v[20:21], v[48:49], -v[30:31]
	v_fma_f64 v[20:21], v[22:23], v[48:49], -v[32:33]
	v_fma_f64 v[22:23], v[24:25], v[48:49], -v[34:35]
	v_fma_f64 v[6:7], v[6:7], v[48:49], -v[36:37]
	v_cvt_f32_f64_e32 v0, v[0:1]
	v_cvt_f32_f64_e32 v1, v[2:3]
	v_cvt_f32_f64_e32 v2, v[4:5]
	v_cvt_f32_f64_e32 v3, v[18:19]
	v_cvt_f32_f64_e32 v4, v[20:21]
	v_cvt_f32_f64_e32 v5, v[22:23]
	v_cvt_f32_f64_e32 v6, v[6:7]
	v_sin_f32_e32 v28, v0
	v_cos_f32_e32 v26, v0
	v_sin_f32_e32 v29, v1
	v_cos_f32_e32 v27, v1
	v_sin_f32_e32 v66, v2
	v_cos_f32_e32 v30, v2
	v_sin_f32_e32 v67, v3
	v_cos_f32_e32 v31, v3
	v_sin_f32_e32 v24, v4
	v_cos_f32_e32 v22, v4
	v_sin_f32_e32 v25, v5
	v_cos_f32_e32 v23, v5
	v_sin_f32_e32 v20, v6
	v_cos_f32_e32 v18, v6
	s_waitcnt vmcnt(5)
	v_lshlrev_b32_e32 v34, 16, v47
	v_and_b32_e32 v35, 0xffff0000, v47
	s_waitcnt vmcnt(4)
	v_lshlrev_b32_e32 v32, 16, v55
	v_and_b32_e32 v33, 0xffff0000, v55
	global_load_dwordx4 v[0:3], v128, s[6:7] offset:272
	global_load_dwordx4 v[4:7], v128, s[6:7] offset:256
	v_lshlrev_b32_e32 v38, 16, v46
	v_and_b32_e32 v39, 0xffff0000, v46
	v_lshlrev_b32_e32 v36, 16, v54
	v_and_b32_e32 v37, 0xffff0000, v54
	v_lshlrev_b32_e32 v42, 16, v45
	v_and_b32_e32 v43, 0xffff0000, v45
	v_lshlrev_b32_e32 v40, 16, v53
	v_and_b32_e32 v41, 0xffff0000, v53
	v_lshlrev_b32_e32 v46, 16, v44
	v_and_b32_e32 v47, 0xffff0000, v44
	v_lshlrev_b32_e32 v44, 16, v52
	v_and_b32_e32 v45, 0xffff0000, v52
	s_waitcnt vmcnt(4)
	v_lshlrev_b32_e32 v104, 16, v63
	v_and_b32_e32 v105, 0xffff0000, v63
	global_load_dwordx4 v[52:55], v128, s[6:7] offset:208
	global_load_dwordx4 v[68:71], v128, s[6:7] offset:192
	v_lshlrev_b32_e32 v108, 16, v62
	v_and_b32_e32 v109, 0xffff0000, v62
	v_lshlrev_b32_e32 v112, 16, v61
	v_and_b32_e32 v113, 0xffff0000, v61
	v_lshlrev_b32_e32 v116, 16, v60
	v_and_b32_e32 v117, 0xffff0000, v60
	v_lshlrev_b32_e32 v120, 16, v59
	v_and_b32_e32 v121, 0xffff0000, v59
	global_load_dwordx4 v[60:63], v128, s[6:7] offset:144
	global_load_dwordx4 v[72:75], v128, s[6:7] offset:128
	v_lshlrev_b32_e32 v124, 16, v58
	v_and_b32_e32 v125, 0xffff0000, v58
	v_lshlrev_b32_e32 v130, 16, v57
	v_and_b32_e32 v131, 0xffff0000, v57
	v_lshlrev_b32_e32 v134, 16, v56
	v_and_b32_e32 v135, 0xffff0000, v56
	global_load_dwordx4 v[56:59], v128, s[6:7] offset:80
	global_load_dwordx4 v[76:79], v128, s[6:7] offset:64
	global_load_dwordx4 v[80:83], v128, s[6:7] offset:16
	global_load_dwordx4 v[84:87], v128, s[6:7]
	s_waitcnt vmcnt(11)
	v_lshlrev_b32_e32 v160, 16, v10
	v_and_b32_e32 v161, 0xffff0000, v10
	v_lshlrev_b32_e32 v156, 16, v11
	v_and_b32_e32 v157, 0xffff0000, v11
	v_pk_mul_f32 v[10:11], v[160:161], v[160:161]
	v_pk_mul_f32 v[158:159], v[156:157], v[156:157]
	v_add_f32_e32 v10, v10, v11
	v_lshlrev_b32_e32 v154, 16, v12
	v_and_b32_e32 v155, 0xffff0000, v12
	v_add_f32_e32 v10, v158, v10
	v_lshlrev_b32_e32 v150, 16, v13
	v_and_b32_e32 v151, 0xffff0000, v13
	v_pk_mul_f32 v[12:13], v[154:155], v[154:155]
	v_add_f32_e32 v10, v159, v10
	v_add_f32_e32 v10, v12, v10
	v_pk_mul_f32 v[152:153], v[150:151], v[150:151]
	v_add_f32_e32 v10, v13, v10
	s_waitcnt vmcnt(10)
; DI float rsqrt_f(float x) { return __builtin_amdgcn_rsqf(x); }
; template <int DK>
; DI void attn_core(const bf16x8 (&qf)[DK / 16], const short* Kg, const short* VTg, size_t ldvt, int ntiles, char* smem,
;                   f32x16 (&O)[2], float& lsum) {
;     ...
;   for (int i = 0; i < NKC; i++) { int c = tid + 512 * i; koff[i] = (c / KCH) * KROW + (c % KCH) * 16; }
;   const int vrow = tid >> 4, vcol = tid & 15;
;   const short* vg = VTg + (size_t)vrow * ldvt + vcol * 8;
;   const int voff = KT_BYTES + vrow * VROW + vcol * 16;
; #pragma unroll
;   for (int i = 0; i < 16; i++) { O[0][i] = 0.f; O[1][i] = 0.f; }
;   float l0 = 0.f;
; DI void mla_item(PRef p, int j, int seq, int head, int qb, char* smem) {
;     ...
;   ss += __shfl_xor(ss, 32);
;   const float f = rsqrt_f(ss * (1.f / 96.f) + EPS);
;   const float sc = 0.10206207261596575f * LOG2E;
; #pragma unroll
;   for (int ks = 0; ks < 6; ks++)
; #pragma unroll
;     for (int e = 0; e < 8; e++) qv[ks][e] *= f * gq[ks * 16 + 8 * h + e];
	v_lshlrev_b32_e32 v148, 16, v14
	v_and_b32_e32 v149, 0xffff0000, v14
	v_add_f32_e32 v10, v152, v10
	v_lshlrev_b32_e32 v144, 16, v15
	v_and_b32_e32 v145, 0xffff0000, v15
	v_pk_mul_f32 v[14:15], v[148:149], v[148:149]
	v_add_f32_e32 v10, v153, v10
	v_add_f32_e32 v10, v14, v10
	v_pk_mul_f32 v[146:147], v[144:145], v[144:145]
	v_add_f32_e32 v10, v15, v10
	v_lshlrev_b32_e32 v142, 16, v16
	v_and_b32_e32 v143, 0xffff0000, v16
	v_add_f32_e32 v10, v146, v10
	v_lshlrev_b32_e32 v138, 16, v17
	v_and_b32_e32 v139, 0xffff0000, v17
	v_pk_mul_f32 v[16:17], v[142:143], v[142:143]
	v_add_f32_e32 v10, v147, v10
	v_add_f32_e32 v10, v16, v10
	v_pk_mul_f32 v[140:141], v[138:139], v[138:139]
	v_add_f32_e32 v10, v17, v10
	v_add_f32_e32 v10, v140, v10
	v_pk_mul_f32 v[136:137], v[134:135], v[134:135]
	v_add_f32_e32 v10, v141, v10
	v_add_f32_e32 v10, v136, v10
	v_pk_mul_f32 v[132:133], v[130:131], v[130:131]
	v_add_f32_e32 v10, v137, v10
	v_add_f32_e32 v10, v132, v10
	v_pk_mul_f32 v[126:127], v[124:125], v[124:125]
	v_add_f32_e32 v10, v133, v10
	v_add_f32_e32 v10, v126, v10
	v_pk_mul_f32 v[122:123], v[120:121], v[120:121]
	v_add_f32_e32 v10, v127, v10
	v_add_f32_e32 v10, v122, v10
	v_pk_mul_f32 v[118:119], v[116:117], v[116:117]
	v_add_f32_e32 v10, v123, v10
	v_add_f32_e32 v10, v118, v10
	v_pk_mul_f32 v[114:115], v[112:113], v[112:113]
	v_add_f32_e32 v10, v119, v10
	v_add_f32_e32 v10, v114, v10
	v_pk_mul_f32 v[110:111], v[108:109], v[108:109]
	v_add_f32_e32 v10, v115, v10
	v_add_f32_e32 v10, v110, v10
	v_pk_mul_f32 v[106:107], v[104:105], v[104:105]
	v_add_f32_e32 v10, v111, v10
	v_add_f32_e32 v10, v106, v10
	v_pk_mul_f32 v[98:99], v[46:47], v[46:47]
	v_add_f32_e32 v10, v107, v10
	v_add_f32_e32 v10, v98, v10
	v_pk_mul_f32 v[94:95], v[42:43], v[42:43]
	v_add_f32_e32 v10, v99, v10
	v_add_f32_e32 v10, v94, v10
	v_pk_mul_f32 v[90:91], v[38:39], v[38:39]
	v_add_f32_e32 v10, v95, v10
	v_add_f32_e32 v10, v90, v10
	v_pk_mul_f32 v[64:65], v[34:35], v[34:35]
	v_add_f32_e32 v10, v91, v10
	v_add_f32_e32 v10, v64, v10
	v_pk_mul_f32 v[100:101], v[44:45], v[44:45]
	v_add_f32_e32 v10, v65, v10
	v_add_f32_e32 v10, v100, v10
	v_pk_mul_f32 v[96:97], v[40:41], v[40:41]
	v_add_f32_e32 v10, v101, v10
	v_add_f32_e32 v10, v96, v10
	v_pk_mul_f32 v[92:93], v[36:37], v[36:37]
	v_add_f32_e32 v10, v97, v10
	v_add_f32_e32 v10, v92, v10
	v_pk_mul_f32 v[88:89], v[32:33], v[32:33]
	v_add_f32_e32 v10, v93, v10
	v_add_f32_e32 v10, v88, v10
	v_add_f32_e32 v12, v89, v10
	ds_bpermute_b32 v13, v103, v12
	v_mul_f64 v[50:51], v[8:9], v[48:49]
	v_floor_f64_e32 v[10:11], v[50:51]
	v_fma_f64 v[8:9], v[8:9], v[48:49], -v[10:11]
	v_cvt_f32_f64_e32 v8, v[8:9]
	s_waitcnt lgkmcnt(0)
	v_add_f32_e32 v9, v12, v13
	v_fmamk_f32 v9, v9, 0x3c2aaaab, v198
	v_rsq_f32_e32 v100, v9
	global_load_dwordx4 v[48:51], v128, s[6:7] offset:336
	global_load_dwordx4 v[88:91], v128, s[6:7] offset:320
	v_sin_f32_e32 v21, v8
	v_cos_f32_e32 v19, v8
	s_waitcnt vmcnt(2)
	v_pk_mul_f32 v[8:9], v[84:85], v[100:101] op_sel_hi:[1,0]
	v_pk_mul_f32 v[10:11], v[52:53], v[100:101] op_sel_hi:[1,0]
	v_pk_mul_f32 v[106:107], v[8:9], v[160:161]
	v_pk_mul_f32 v[8:9], v[86:87], v[100:101] op_sel_hi:[1,0]
	v_mov_b32_e32 v160, v196
	v_pk_mul_f32 v[126:127], v[8:9], v[156:157]
	v_pk_mul_f32 v[8:9], v[80:81], v[100:101] op_sel_hi:[1,0]
	v_pk_mul_f32 v[12:13], v[54:55], v[100:101] op_sel_hi:[1,0]
	v_pk_mul_f32 v[132:133], v[8:9], v[154:155]
	v_pk_mul_f32 v[8:9], v[82:83], v[100:101] op_sel_hi:[1,0]
	v_lshlrev_b32_e32 v52, 4, v160
	v_pk_mul_f32 v[136:137], v[8:9], v[150:151]
	v_pk_mul_f32 v[8:9], v[76:77], v[100:101] op_sel_hi:[1,0]
	v_pk_mul_f32 v[4:5], v[4:5], v[100:101] op_sel_hi:[1,0]
	v_pk_mul_f32 v[140:141], v[8:9], v[148:149]
	v_pk_mul_f32 v[8:9], v[78:79], v[100:101] op_sel_hi:[1,0]
	v_and_b32_e32 v128, 0xf0, v52
	v_pk_mul_f32 v[144:145], v[8:9], v[144:145]
	v_pk_mul_f32 v[8:9], v[56:57], v[100:101] op_sel_hi:[1,0]
	v_mov_b64_e32 v[52:53], s[28:29]
	v_pk_mul_f32 v[56:57], v[8:9], v[142:143]
	v_pk_mul_f32 v[8:9], v[58:59], v[100:101] op_sel_hi:[1,0]
	s_mov_b32 s28, 0x28000
	v_pk_mul_f32 v[58:59], v[8:9], v[138:139]
	v_pk_mul_f32 v[8:9], v[72:73], v[100:101] op_sel_hi:[1,0]
	v_lshlrev_b32_e32 v92, 3, v160
	v_pk_mul_f32 v[134:135], v[8:9], v[134:135]
	v_pk_mul_f32 v[8:9], v[74:75], v[100:101] op_sel_hi:[1,0]
	v_add_u32_e32 v94, 0x1000, v92
	v_pk_mul_f32 v[130:131], v[8:9], v[130:131]
	v_pk_mul_f32 v[8:9], v[60:61], v[100:101] op_sel_hi:[1,0]
	v_add_u32_e32 v96, 0x2000, v92
	v_pk_mul_f32 v[14:15], v[8:9], v[124:125]
	v_pk_mul_f32 v[8:9], v[62:63], v[100:101] op_sel_hi:[1,0]
	v_ashrrev_i32_e32 v93, 31, v92
	v_pk_mul_f32 v[16:17], v[8:9], v[120:121]
	v_pk_mul_f32 v[8:9], v[68:69], v[100:101] op_sel_hi:[1,0]
	v_ashrrev_i32_e32 v95, 31, v94
	v_pk_mul_f32 v[60:61], v[8:9], v[116:117]
	v_pk_mul_f32 v[8:9], v[70:71], v[100:101] op_sel_hi:[1,0]
	v_ashrrev_i32_e32 v101, 4, v160
	v_mad_i64_i32 v[52:53], s[28:29], v101, s28, v[52:53]
	v_ashrrev_i32_e32 v97, 31, v96
	s_add_u32 s28, s8, 0x6000
	v_pk_mul_f32 v[10:11], v[10:11], v[108:109]
	v_pk_mul_f32 v[12:13], v[12:13], v[104:105]
	v_lshlrev_b64 v[54:55], 1, v[92:93]
	v_lshlrev_b64 v[104:105], 1, v[94:95]
	v_lshlrev_b64 v[108:109], 1, v[96:97]
	v_lshl_add_u64 v[98:99], v[52:53], 0, v[128:129]
	s_addc_u32 s29, s9, 0
	v_lshl_add_u64 v[62:63], s[8:9], 0, v[54:55]
	v_lshl_add_u64 v[68:69], s[8:9], 0, v[104:105]
	v_lshl_add_u64 v[76:77], s[8:9], 0, v[108:109]
	v_add_co_u32_e32 v52, vcc, s37, v98
	v_lshl_add_u64 v[54:55], s[28:29], 0, v[54:55]
	global_load_dwordx4 v[62:65], v[62:63], off
	s_nop 0
	global_load_dwordx4 v[68:71], v[68:69], off
	v_addc_co_u32_e32 v53, vcc, 0, v99, vcc
	global_load_dwordx4 v[72:75], v[98:99], off
	s_nop 0
	global_load_dwordx4 v[76:79], v[76:77], off
	s_nop 0
	global_load_dwordx4 v[80:83], v[52:53], off
	global_load_dwordx4 v[84:87], v[54:55], off
	v_lshl_add_u64 v[54:55], s[28:29], 0, v[104:105]
	v_pk_mul_f32 v[8:9], v[8:9], v[112:113]
	v_lshl_add_u64 v[104:105], s[28:29], 0, v[108:109]
	global_load_dwordx4 v[108:111], v[54:55], off
	global_load_dwordx4 v[112:115], v[104:105], off
	global_load_dwordx4 v[116:119], v[98:99], off offset:256
	global_load_dwordx4 v[120:123], v[52:53], off offset:256
	v_pk_mul_f32 v[0:1], v[0:1], v[100:101] op_sel_hi:[1,0]
	v_pk_mul_f32 v[124:125], v[4:5], v[46:47]
	v_pk_mul_f32 v[142:143], v[0:1], v[38:39]
	v_pk_mul_f32 v[0:1], v[2:3], v[100:101] op_sel_hi:[1,0]
	v_pk_mul_f32 v[4:5], v[6:7], v[100:101] op_sel_hi:[1,0]
	v_pk_mul_f32 v[146:147], v[0:1], v[34:35]
	v_pk_mul_f32 v[138:139], v[4:5], v[42:43]
	v_mul_hi_i32 v3, v160, s41
	s_waitcnt vmcnt(10)
; #define KLOAD(kf_, base)                                                                       \
;   { _Pragma("unroll") for (int ks = 0; ks < NKS; ks++) kf_[ks] = *(const bf16x8*)((base) + kfo + ks * 32); }
; #define QKM(dst, kf_)                                                                          \
;   {                                                                                            \
;     _Pragma("unroll") for (int i = 0; i < 16; i++) dst[i] = 0.f;                               \
;     _Pragma("unroll") for (int ks = 0; ks < NKS; ks++) dst = MFMA(kf_[ks], qf[ks], dst);       \
;   }
; template <int DK>
; DI void attn_core(const bf16x8 (&qf)[DK / 16], const short* Kg, const short* VTg, size_t ldvt, int ntiles, char* smem,
;                   f32x16 (&O)[2], float& lsum) {
;     ...
;   const int kfo = pr * KROW + h * 16;
;   const int vfo = KT_BYTES + r * VROW + h * 16;
;   AGLOAD(0);
;   ASTORE(0);
;   AGLOAD(ntiles > 1 ? 1 : 0);
;   ASTORE(1);
;   __syncthreads();
;   f32x16 Sc;
;   {
;     bf16x8 kf[NKS];
;     KLOAD(kf, smem);
;     QKM(Sc, kf);
; DI void mla_item(PRef p, int j, int seq, int head, int qb, char* smem) {
;     ...
;   for (int e = 0; e < 8; e++) {
;     float cs, sn;
;     rope_cs(pos, 8 * h + e, cs, sn);
;     float x1 = qv[4][e], x2 = qv[5][e];
;     qv[4][e] = x1 * cs - x2 * sn;
;     qv[5][e] = x1 * sn + x2 * cs;
;   }
;   bf16x8 qf[6];
; #pragma unroll
;   for (int ks = 0; ks < 6; ks++) {
;     u32x4 t;
; #pragma unroll
;     for (int e = 0; e < 4; e++) t[e] = pack_bf16(qv[ks][2 * e] * sc, qv[ks][2 * e + 1] * sc);
;     qf[ks] = __builtin_bit_cast(bf16x8, t);
;   }
	v_pk_mul_f32 v[0:1], v[88:89], v[100:101] op_sel_hi:[1,0]
	v_lshrrev_b32_e32 v6, 31, v3
	v_pk_mul_f32 v[88:89], v[0:1], v[44:45]
	v_pk_mul_f32 v[0:1], v[90:91], v[100:101] op_sel_hi:[1,0]
	v_lshrrev_b32_e32 v3, 1, v3
	v_pk_mul_f32 v[90:91], v[0:1], v[40:41]
	v_pk_mul_f32 v[0:1], v[48:49], v[100:101] op_sel_hi:[1,0]
	v_add_u32_e32 v3, v3, v6
	v_pk_mul_f32 v[148:149], v[0:1], v[36:37]
	v_pk_mul_f32 v[0:1], v[50:51], v[100:101] op_sel_hi:[1,0]
	v_add_lshl_u32 v104, v3, v160, 4
	v_pk_mul_f32 v[150:151], v[0:1], v[32:33]
	v_pk_mul_f32 v[0:1], v[88:89], v[26:27]
	v_add_u32_e32 v3, 0x200, v160
	v_pk_fma_f32 v[152:153], v[124:125], v[28:29], v[0:1]
	v_pk_mul_f32 v[0:1], v[90:91], v[30:31]
	v_mul_hi_i32 v6, v3, s41
	v_pk_fma_f32 v[154:155], v[138:139], v[66:67], v[0:1]
	v_pk_mul_f32 v[0:1], v[148:149], v[22:23]
	v_lshrrev_b32_e32 v7, 31, v6
	v_pk_fma_f32 v[156:157], v[142:143], v[24:25], v[0:1]
	v_pk_mul_f32 v[0:1], v[150:151], v[18:19]
	v_lshrrev_b32_e32 v6, 1, v6
	v_pk_fma_f32 v[158:159], v[146:147], v[20:21], v[0:1]
	v_pk_mul_f32 v[0:1], v[106:107], s[30:31] op_sel_hi:[1,0]
	v_add_u32_e32 v6, v6, v7
	v_cvt_pk_bf16_f32 v48, v0, v1
	v_pk_mul_f32 v[0:1], v[126:127], s[30:31] op_sel_hi:[1,0]
	v_add_lshl_u32 v105, v6, v3, 4
	v_cvt_pk_bf16_f32 v49, v0, v1
	v_pk_mul_f32 v[0:1], v[132:133], s[30:31] op_sel_hi:[1,0]
	v_add_u32_e32 v3, 0x400, v160
	v_cvt_pk_bf16_f32 v50, v0, v1
	v_pk_mul_f32 v[0:1], v[136:137], s[30:31] op_sel_hi:[1,0]
	v_mul_hi_i32 v6, v3, s41
	v_cvt_pk_bf16_f32 v51, v0, v1
	v_pk_mul_f32 v[0:1], v[140:141], s[30:31] op_sel_hi:[1,0]
	v_lshrrev_b32_e32 v7, 31, v6
	v_cvt_pk_bf16_f32 v52, v0, v1
	v_pk_mul_f32 v[0:1], v[144:145], s[30:31] op_sel_hi:[1,0]
	v_lshrrev_b32_e32 v6, 1, v6
	v_cvt_pk_bf16_f32 v53, v0, v1
	v_pk_mul_f32 v[0:1], v[56:57], s[30:31] op_sel_hi:[1,0]
	v_add_u32_e32 v6, v6, v7
	v_cvt_pk_bf16_f32 v54, v0, v1
	v_pk_mul_f32 v[0:1], v[58:59], s[30:31] op_sel_hi:[1,0]
	v_add_lshl_u32 v106, v6, v3, 4
	v_cvt_pk_bf16_f32 v55, v0, v1
	v_pk_mul_f32 v[0:1], v[134:135], s[30:31] op_sel_hi:[1,0]
	v_and_b32_e32 v3, 19, v160
	v_cvt_pk_bf16_f32 v56, v0, v1
	v_lshlrev_b32_e32 v0, 1, v160
	v_lshrrev_b32_e32 v1, 1, v160
	v_and_b32_e32 v0, 8, v0
	v_and_b32_e32 v2, 4, v1
	v_and_b32_e32 v126, 16, v1
	v_or3_b32 v0, v3, v0, v2
	s_movk_i32 s28, 0xd0
	v_mad_u32_u24 v107, v0, s28, v126
	v_mad_u64_u32 v[100:101], s[28:29], v101, s36, v[128:129]
	v_add_u32_e32 v0, 0x6800, v100
	s_waitcnt vmcnt(9)
	ds_write_b128 v104, v[62:65]
	s_waitcnt vmcnt(8)
	ds_write_b128 v105, v[68:71]
	s_waitcnt vmcnt(6)
	ds_write_b128 v106, v[76:79]
	ds_write_b128 v100, v[72:75] offset:26624
	s_waitcnt vmcnt(5)
	ds_write_b128 v100, v[80:83] offset:35328
	s_waitcnt vmcnt(4)
	ds_write_b128 v104, v[84:87] offset:44032
	s_waitcnt vmcnt(3)
	ds_write_b128 v105, v[108:111] offset:44032
	s_waitcnt vmcnt(2)
	ds_write_b128 v106, v[112:115] offset:44032
	s_waitcnt vmcnt(1)
	ds_write_b128 v0, v[116:119] offset:44032
	s_waitcnt vmcnt(0)
	ds_write_b128 v0, v[120:123] offset:52736
	s_waitcnt lgkmcnt(0)
	s_barrier
	ds_read_b128 v[0:3], v107
	v_pk_mul_f32 v[4:5], v[130:131], s[30:31] op_sel_hi:[1,0]
	v_mov_b32_e32 v108, 0
	v_cvt_pk_bf16_f32 v57, v4, v5
	v_pk_mul_f32 v[4:5], v[14:15], s[30:31] op_sel_hi:[1,0]
	s_mov_b32 s28, 0
	v_cvt_pk_bf16_f32 v58, v4, v5
	v_pk_mul_f32 v[4:5], v[16:17], s[30:31] op_sel_hi:[1,0]
	v_mov_b32_e32 v14, v108
	v_cvt_pk_bf16_f32 v59, v4, v5
	v_pk_mul_f32 v[4:5], v[60:61], s[30:31] op_sel_hi:[1,0]
	v_mov_b32_e32 v15, v108
	v_cvt_pk_bf16_f32 v60, v4, v5
	ds_read_b128 v[4:7], v107 offset:32
	s_waitcnt lgkmcnt(1)
	v_mfma_f32_32x32x16_bf16 v[32:47], v[0:3], v[48:51], 0
	v_mul_f32_e64 v0, v8, s30
	v_mul_f32_e64 v1, v9, s30
	v_mov_b32_e32 v16, 0
	v_cvt_pk_bf16_f32 v61, v0, v1
	v_mul_f32_e64 v0, v10, s30
	v_mul_f32_e64 v1, v11, s30
	v_mov_b32_e32 v10, v108
	v_cvt_pk_bf16_f32 v62, v0, v1
	v_pk_mul_f32 v[0:1], v[12:13], s[30:31] op_sel_hi:[1,0]
	s_waitcnt lgkmcnt(0)
	v_mfma_f32_32x32x16_bf16 v[32:47], v[4:7], v[52:55], v[32:47]
	v_cvt_pk_bf16_f32 v63, v0, v1
	ds_read_b128 v[0:3], v107 offset:64
	v_mul_f32_e64 v4, v88, v28
	v_mul_f32_e64 v5, v89, v29
	v_mov_b32_e32 v11, v108
	v_pk_fma_f32 v[4:5], v[124:125], v[26:27], v[4:5] neg_lo:[0,0,1] neg_hi:[0,0,1]
	v_mov_b32_e32 v12, v108
	v_pk_mul_f32 v[4:5], v[4:5], s[30:31] op_sel_hi:[1,0]
	v_mov_b32_e32 v13, v108
	v_cvt_pk_bf16_f32 v64, v4, v5
	v_pk_mul_f32 v[4:5], v[90:91], v[66:67]
	v_mov_b32_e32 v17, v108
	v_pk_fma_f32 v[8:9], v[138:139], v[30:31], v[4:5] neg_lo:[0,0,1] neg_hi:[0,0,1]
	ds_read_b128 v[4:7], v107 offset:96
	s_waitcnt lgkmcnt(1)
	v_mfma_f32_32x32x16_bf16 v[32:47], v[0:3], v[56:59], v[32:47]
	v_mul_f32_e64 v0, v8, s30
	v_mul_f32_e64 v1, v9, s30
	v_mov_b32_e32 v8, v108
	v_cvt_pk_bf16_f32 v65, v0, v1
	v_mul_f32_e64 v0, v148, v24
	v_mul_f32_e64 v1, v149, v25
	v_mov_b32_e32 v9, v108
	v_pk_fma_f32 v[0:1], v[142:143], v[22:23], v[0:1] neg_lo:[0,0,1] neg_hi:[0,0,1]
	v_mov_b32_e32 v22, v108
	v_pk_mul_f32 v[0:1], v[0:1], s[30:31] op_sel_hi:[1,0]
	s_waitcnt lgkmcnt(0)
	v_mfma_f32_32x32x16_bf16 v[32:47], v[4:7], v[60:63], v[32:47]
	v_cvt_pk_bf16_f32 v66, v0, v1
	ds_read_b128 v[0:3], v107 offset:128
	v_mul_f32_e64 v4, v150, v20
	v_mul_f32_e64 v5, v151, v21
	v_mov_b32_e32 v20, v108
	v_pk_fma_f32 v[4:5], v[146:147], v[18:19], v[4:5] neg_lo:[0,0,1] neg_hi:[0,0,1]
	v_mov_b32_e32 v18, v108
	v_pk_mul_f32 v[4:5], v[4:5], s[30:31] op_sel_hi:[1,0]
	v_mov_b32_e32 v19, v108
	v_cvt_pk_bf16_f32 v67, v4, v5
	v_pk_mul_f32 v[4:5], v[152:153], s[30:31] op_sel_hi:[1,0]
	v_mov_b32_e32 v21, v108
	v_cvt_pk_bf16_f32 v68, v4, v5
	ds_read_b128 v[4:7], v107 offset:160
	s_waitcnt lgkmcnt(1)
; #define KLOAD(kf_, base)                                                                       \
;   { _Pragma("unroll") for (int ks = 0; ks < NKS; ks++) kf_[ks] = *(const bf16x8*)((base) + kfo + ks * 32); }
; #define VLOAD(vf_, base)                                                                       \
;   { _Pragma("unroll") for (int q = 0; q < 4; q++) vf_[q] = *(const bf16x8*)((base) + vfo + (q >> 1) * 32 * VROW + (q & 1) * 32); }
; #define QKM(dst, kf_)                                                                          \
;   {                                                                                            \
;     _Pragma("unroll") for (int i = 0; i < 16; i++) dst[i] = 0.f;                               \
;     _Pragma("unroll") for (int ks = 0; ks < NKS; ks++) dst = MFMA(kf_[ks], qf[ks], dst);       \
;   }
; #define SB() __builtin_amdgcn_sched_barrier(0)
; template <int DK>
; DI void attn_core(const bf16x8 (&qf)[DK / 16], const short* Kg, const short* VTg, size_t ldvt, int ntiles, char* smem,
;                   f32x16 (&O)[2], float& lsum) {
;     ...
;   for (int t = 0; t < ntiles; t++) {
;     const int tn = t + 2 < ntiles ? t + 2 : ntiles - 1;
;     AGLOAD(tn);
;     const char* cur = smem + sc * ST;
;     const char* nxt = smem + sn * ST;
;     f32x16 Sn;
;     bf16x8 pa, pb, qa, qb;
;     bf16x8 kf[NKS], vf[4];
;     KLOAD(kf, cur + 32 * KROW);
;     SB();
;     SOFTMAX(Sc, pa, pb, l0);
;     SB();
;     QKM(Sn, kf);
;     SB();
;     KLOAD(kf, cur + 64 * KROW);
;     VLOAD(vf, cur);
;     SB();
;     SOFTMAX(Sn, qa, qb, l0);
;     SB();
;     QKM(Sc, kf);
;     PVM(vf, pa, pb);
;     SB();
	v_mfma_f32_32x32x16_bf16 v[32:47], v[0:3], v[64:67], v[32:47]
	v_mul_f32_e64 v0, v154, s30
	v_mul_f32_e64 v1, v155, s30
	v_mov_b32_e32 v2, v108
	v_cvt_pk_bf16_f32 v69, v0, v1
	v_mul_f32_e64 v0, v156, s30
	v_mul_f32_e64 v1, v157, s30
	v_mov_b32_e32 v3, v108
	v_cvt_pk_bf16_f32 v70, v0, v1
	v_pk_mul_f32 v[0:1], v[158:159], s[30:31] op_sel_hi:[1,0]
	v_mov_b32_e32 v23, v108
	v_cvt_pk_bf16_f32 v71, v0, v1
	v_and_b32_e32 v0, 31, v160
	v_mad_u32_u24 v101, v0, s36, v126
	s_waitcnt lgkmcnt(0)
	v_mfma_f32_32x32x16_bf16 v[32:47], v[4:7], v[68:71], v[32:47]
	v_mov_b32_e32 v0, 0
	v_mov_b32_e32 v1, v108
	v_mov_b32_e32 v4, v108
	v_mov_b32_e32 v5, v108
	v_mov_b32_e32 v6, v108
	v_mov_b32_e32 v7, v108
	v_mov_b32_e32 v24, v108
	v_mov_b32_e32 v25, v108
	v_mov_b32_e32 v26, v108
	v_mov_b32_e32 v27, v108
	v_mov_b32_e32 v28, v108
	v_mov_b32_e32 v29, v108
	v_mov_b32_e32 v30, v108
	v_mov_b32_e32 v31, v108
	v_mov_b32_e32 v162, 0
	v_mov_b32_e32 v163, 0
	v_mov_b32_e32 v164, 0
	v_mov_b32_e32 v165, 0
	v_mov_b32_e32 v166, 0
	v_mov_b32_e32 v167, 0
	v_mov_b32_e32 v168, 0
	v_mov_b32_e32 v169, 0
	v_mov_b32_e32 v138, 0
	v_mov_b32_e32 v139, 0
	v_mov_b32_e32 v140, 0
	v_mov_b32_e32 v141, 0
	v_mov_b32_e32 v142, 0
	v_mov_b32_e32 v143, 0
	v_mov_b32_e32 v144, 0
	v_mov_b32_e32 v145, 0
	v_mov_b32_e32 v146, 0
	v_mov_b32_e32 v147, 0
	v_mov_b32_e32 v148, 0
	v_mov_b32_e32 v149, 0
	v_mov_b32_e32 v150, 0
	v_mov_b32_e32 v151, 0
	v_mov_b32_e32 v152, 0
	v_mov_b32_e32 v153, 0
	ds_read_b128 v[110:113], v107 offset:6656
	ds_read_b128 v[114:117], v107 offset:6688
	ds_read_b128 v[118:121], v107 offset:6720
	ds_read_b128 v[122:125], v107 offset:6752
	ds_read_b128 v[130:133], v107 offset:6784
	ds_read_b128 v[134:137], v107 offset:6816
	s_waitcnt lgkmcnt(0)
	s_min_u32 s29, s21, 0x7d
	s_add_i32 s29, s29, 2
	s_mul_i32 s34, s29, 0x6000
	s_add_u32 s34, s8, s34
	s_addc_u32 s35, s9, 0
	s_lshl_b32 s30, s29, 8
	s_mul_i32 s29, s28, 0xac00
	v_add_u32_e32 v128, s29, v107
	v_add_u32_e32 v170, s29, v101
	s_mul_i32 s29, s22, 0xac00
	v_add_u32_e32 v109, s29, v107
.Lmla_prompt_loop:
	s_waitcnt lgkmcnt(6)
	v_mfma_f32_32x32x16_bf16 v[172:187], v[110:113], v[48:51], 0
	ds_read_b128 v[110:113], v128 offset:13312
	v_exp_f32_e32 v32, v32
	v_exp_f32_e32 v33, v33
	v_add_f32_e32 v108, v32, v108
	v_exp_f32_e32 v34, v34
	v_lshl_add_u64 v[188:189], v[92:93], 1, s[34:35]
	global_load_dwordx4 v[84:87], v[188:189], off
	s_waitcnt lgkmcnt(5)
	v_mfma_f32_32x32x16_bf16 v[172:187], v[114:117], v[52:55], v[172:187]
	ds_read_b128 v[114:117], v128 offset:13344
	v_add_f32_e32 v108, v33, v108
	v_cvt_pk_bf16_f32 v154, v32, v33
	v_exp_f32_e32 v35, v35
	v_add_f32_e32 v108, v34, v108
	v_lshl_add_u64 v[190:191], v[94:95], 1, s[34:35]
	global_load_dwordx4 v[72:75], v[190:191], off
	s_waitcnt lgkmcnt(5)
	v_mfma_f32_32x32x16_bf16 v[172:187], v[118:121], v[56:59], v[172:187]
	ds_read_b128 v[118:121], v128 offset:13376
	v_exp_f32_e32 v36, v36
	v_add_f32_e32 v108, v35, v108
	v_cvt_pk_bf16_f32 v155, v34, v35
	v_exp_f32_e32 v37, v37
	v_lshl_add_u64 v[192:193], v[96:97], 1, s[34:35]
	global_load_dwordx4 v[76:79], v[192:193], off
	s_waitcnt lgkmcnt(5)
	v_mfma_f32_32x32x16_bf16 v[172:187], v[122:125], v[60:63], v[172:187]
	ds_read_b128 v[122:125], v128 offset:13408
	v_add_f32_e32 v108, v36, v108
	v_exp_f32_e32 v38, v38
	v_add_f32_e32 v108, v37, v108
	v_cvt_pk_bf16_f32 v156, v36, v37
	v_lshl_add_u64 v[188:189], v[98:99], 0, s[30:31]
	global_load_dwordx4 v[80:83], v[188:189], off
	s_add_u32 s30, s30, s37
	s_waitcnt lgkmcnt(5)
	v_mfma_f32_32x32x16_bf16 v[172:187], v[130:133], v[64:67], v[172:187]
	ds_read_b128 v[130:133], v128 offset:13440
	v_exp_f32_e32 v39, v39
	v_add_f32_e32 v108, v38, v108
	v_exp_f32_e32 v40, v40
	v_add_f32_e32 v108, v39, v108
	v_lshl_add_u64 v[190:191], v[98:99], 0, s[30:31]
	global_load_dwordx4 v[88:91], v[190:191], off
	s_mul_i32 s29, s23, 0xac00
	s_waitcnt lgkmcnt(5)
	v_mfma_f32_32x32x16_bf16 v[172:187], v[134:137], v[68:71], v[172:187]
	ds_read_b128 v[134:137], v128 offset:13472
	v_cvt_pk_bf16_f32 v157, v38, v39
	v_exp_f32_e32 v41, v41
	v_add_f32_e32 v108, v40, v108
	v_exp_f32_e32 v42, v42
	s_waitcnt lgkmcnt(14)
	v_mfma_f32_32x32x16_bf16 v[0:15], v[138:141], v[162:165], v[0:15]
	ds_read_b128 v[138:141], v170 offset:26624
	v_add_f32_e32 v108, v41, v108
	v_cvt_pk_bf16_f32 v158, v40, v41
	v_exp_f32_e32 v43, v43
	v_add_f32_e32 v108, v42, v108
	s_waitcnt lgkmcnt(14)
	v_mfma_f32_32x32x16_bf16 v[16:31], v[146:149], v[162:165], v[16:31]
	ds_read_b128 v[146:149], v170 offset:35328
	v_exp_f32_e32 v44, v44
	v_add_f32_e32 v108, v43, v108
	v_cvt_pk_bf16_f32 v159, v42, v43
	v_exp_f32_e32 v45, v45
	s_waitcnt lgkmcnt(14)
	v_mfma_f32_32x32x16_bf16 v[0:15], v[142:145], v[166:169], v[0:15]
	ds_read_b128 v[142:145], v170 offset:26656
	v_add_f32_e32 v108, v44, v108
	v_exp_f32_e32 v46, v46
	v_add_f32_e32 v108, v45, v108
	v_cvt_pk_bf16_f32 v160, v44, v45
	s_waitcnt lgkmcnt(14)
	v_mfma_f32_32x32x16_bf16 v[16:31], v[150:153], v[166:169], v[16:31]
	ds_read_b128 v[150:153], v170 offset:35360
	v_exp_f32_e32 v47, v47
	v_add_f32_e32 v108, v46, v108
	v_add_f32_e32 v108, v47, v108
	v_cvt_pk_bf16_f32 v161, v46, v47
	s_waitcnt lgkmcnt(9)
	v_mfma_f32_32x32x16_bf16 v[32:47], v[110:113], v[48:51], 0
	ds_read_b128 v[110:113], v128 offset:19968
	v_exp_f32_e32 v172, v172
	v_exp_f32_e32 v173, v173
	v_add_f32_e32 v108, v172, v108
	v_exp_f32_e32 v174, v174
	s_waitcnt lgkmcnt(9)
	v_mfma_f32_32x32x16_bf16 v[32:47], v[114:117], v[52:55], v[32:47]
	ds_read_b128 v[114:117], v128 offset:20000
	v_add_f32_e32 v108, v173, v108
	v_cvt_pk_bf16_f32 v162, v172, v173
	v_exp_f32_e32 v175, v175
	v_add_f32_e32 v108, v174, v108
	s_waitcnt lgkmcnt(9)
; #define KLOAD(kf_, base)                                                                       \
;   { _Pragma("unroll") for (int ks = 0; ks < NKS; ks++) kf_[ks] = *(const bf16x8*)((base) + kfo + ks * 32); }
; #define VLOAD(vf_, base)                                                                       \
;   { _Pragma("unroll") for (int q = 0; q < 4; q++) vf_[q] = *(const bf16x8*)((base) + vfo + (q >> 1) * 32 * VROW + (q & 1) * 32); }
; #define QKM(dst, kf_)                                                                          \
;   {                                                                                            \
;     _Pragma("unroll") for (int i = 0; i < 16; i++) dst[i] = 0.f;                               \
;     _Pragma("unroll") for (int ks = 0; ks < NKS; ks++) dst = MFMA(kf_[ks], qf[ks], dst);       \
;   }
; #define SB() __builtin_amdgcn_sched_barrier(0)
; template <int DK>
; DI void attn_core(const bf16x8 (&qf)[DK / 16], const short* Kg, const short* VTg, size_t ldvt, int ntiles, char* smem,
;                   f32x16 (&O)[2], float& lsum) {
;     ...
;     QKM(Sn, kf);
;     SB();
;     KLOAD(kf, cur + 64 * KROW);
;     VLOAD(vf, cur);
;     SB();
;     SOFTMAX(Sn, qa, qb, l0);
;     SB();
;     QKM(Sc, kf);
;     PVM(vf, pa, pb);
;     SB();
;     KLOAD(kf, cur + 96 * KROW);
;     VLOAD(vf, cur + 64);
;     SB();
;     SOFTMAX(Sc, pa, pb, l0);
;     SB();
;     QKM(Sn, kf);
;     PVM(vf, qa, qb);
;     SB();
;     KLOAD(kf, nxt);
;     VLOAD(vf, cur + 128);
;     SB();
;     SOFTMAX(Sn, qa, qb, l0);
;     SB();
;     QKM(Sc, kf);
;     PVM(vf, pa, pb);
	v_mfma_f32_32x32x16_bf16 v[32:47], v[118:121], v[56:59], v[32:47]
	ds_read_b128 v[118:121], v128 offset:20032
	v_exp_f32_e32 v176, v176
	v_add_f32_e32 v108, v175, v108
	v_cvt_pk_bf16_f32 v163, v174, v175
	v_exp_f32_e32 v177, v177
	s_waitcnt lgkmcnt(9)
	v_mfma_f32_32x32x16_bf16 v[32:47], v[122:125], v[60:63], v[32:47]
	ds_read_b128 v[122:125], v128 offset:20064
	v_add_f32_e32 v108, v176, v108
	v_exp_f32_e32 v178, v178
	v_add_f32_e32 v108, v177, v108
	v_cvt_pk_bf16_f32 v164, v176, v177
	s_waitcnt lgkmcnt(9)
	v_mfma_f32_32x32x16_bf16 v[32:47], v[130:133], v[64:67], v[32:47]
	ds_read_b128 v[130:133], v128 offset:20096
	v_exp_f32_e32 v179, v179
	v_add_f32_e32 v108, v178, v108
	v_exp_f32_e32 v180, v180
	v_add_f32_e32 v108, v179, v108
	s_waitcnt lgkmcnt(9)
	v_mfma_f32_32x32x16_bf16 v[32:47], v[134:137], v[68:71], v[32:47]
	ds_read_b128 v[134:137], v128 offset:20128
	v_cvt_pk_bf16_f32 v165, v178, v179
	v_exp_f32_e32 v181, v181
	v_add_f32_e32 v108, v180, v108
	v_exp_f32_e32 v182, v182
	s_waitcnt lgkmcnt(9)
	v_mfma_f32_32x32x16_bf16 v[0:15], v[138:141], v[154:157], v[0:15]
	ds_read_b128 v[138:141], v170 offset:26688
	v_add_f32_e32 v108, v181, v108
	v_cvt_pk_bf16_f32 v166, v180, v181
	v_exp_f32_e32 v183, v183
	v_add_f32_e32 v108, v182, v108
	s_waitcnt lgkmcnt(9)
	v_mfma_f32_32x32x16_bf16 v[16:31], v[146:149], v[154:157], v[16:31]
	ds_read_b128 v[146:149], v170 offset:35392
	v_exp_f32_e32 v184, v184
	v_add_f32_e32 v108, v183, v108
	v_cvt_pk_bf16_f32 v167, v182, v183
	v_exp_f32_e32 v185, v185
	s_waitcnt lgkmcnt(9)
	v_mfma_f32_32x32x16_bf16 v[0:15], v[142:145], v[158:161], v[0:15]
	ds_read_b128 v[142:145], v170 offset:26720
	v_add_f32_e32 v108, v184, v108
	v_exp_f32_e32 v186, v186
	v_add_f32_e32 v108, v185, v108
	v_cvt_pk_bf16_f32 v168, v184, v185
	s_waitcnt lgkmcnt(9)
	v_mfma_f32_32x32x16_bf16 v[16:31], v[150:153], v[158:161], v[16:31]
	ds_read_b128 v[150:153], v170 offset:35424
	v_exp_f32_e32 v187, v187
	v_add_f32_e32 v108, v186, v108
	v_add_f32_e32 v108, v187, v108
	v_cvt_pk_bf16_f32 v169, v186, v187
	s_waitcnt lgkmcnt(9)
	v_mfma_f32_32x32x16_bf16 v[172:187], v[110:113], v[48:51], 0
	ds_read_b128 v[110:113], v109 offset:0
	v_exp_f32_e32 v32, v32
	v_exp_f32_e32 v33, v33
	v_add_f32_e32 v108, v32, v108
	v_exp_f32_e32 v34, v34
	s_waitcnt lgkmcnt(9)
	v_mfma_f32_32x32x16_bf16 v[172:187], v[114:117], v[52:55], v[172:187]
	ds_read_b128 v[114:117], v109 offset:32
	v_add_f32_e32 v108, v33, v108
	v_cvt_pk_bf16_f32 v154, v32, v33
	v_exp_f32_e32 v35, v35
	v_add_f32_e32 v108, v34, v108
	s_waitcnt lgkmcnt(9)
	v_mfma_f32_32x32x16_bf16 v[172:187], v[118:121], v[56:59], v[172:187]
	ds_read_b128 v[118:121], v109 offset:64
	v_exp_f32_e32 v36, v36
	v_add_f32_e32 v108, v35, v108
	v_cvt_pk_bf16_f32 v155, v34, v35
	v_exp_f32_e32 v37, v37
	s_waitcnt lgkmcnt(9)
	v_mfma_f32_32x32x16_bf16 v[172:187], v[122:125], v[60:63], v[172:187]
	ds_read_b128 v[122:125], v109 offset:96
	v_add_f32_e32 v108, v36, v108
	v_exp_f32_e32 v38, v38
	v_add_f32_e32 v108, v37, v108
	v_cvt_pk_bf16_f32 v156, v36, v37
	s_waitcnt lgkmcnt(9)
	v_mfma_f32_32x32x16_bf16 v[172:187], v[130:133], v[64:67], v[172:187]
	ds_read_b128 v[130:133], v109 offset:128
	v_exp_f32_e32 v39, v39
	v_add_f32_e32 v108, v38, v108
	v_exp_f32_e32 v40, v40
	v_add_f32_e32 v108, v39, v108
	s_waitcnt lgkmcnt(9)
	v_mfma_f32_32x32x16_bf16 v[172:187], v[134:137], v[68:71], v[172:187]
	ds_read_b128 v[134:137], v109 offset:160
	v_cvt_pk_bf16_f32 v157, v38, v39
	v_exp_f32_e32 v41, v41
	v_add_f32_e32 v108, v40, v108
	v_exp_f32_e32 v42, v42
	s_waitcnt lgkmcnt(9)
	v_mfma_f32_32x32x16_bf16 v[0:15], v[138:141], v[162:165], v[0:15]
	ds_read_b128 v[138:141], v170 offset:26752
	v_add_f32_e32 v108, v41, v108
	v_cvt_pk_bf16_f32 v158, v40, v41
	v_exp_f32_e32 v43, v43
	v_add_f32_e32 v108, v42, v108
	s_waitcnt lgkmcnt(9)
	v_mfma_f32_32x32x16_bf16 v[16:31], v[146:149], v[162:165], v[16:31]
	ds_read_b128 v[146:149], v170 offset:35456
	v_exp_f32_e32 v44, v44
	v_add_f32_e32 v108, v43, v108
	v_cvt_pk_bf16_f32 v159, v42, v43
	v_exp_f32_e32 v45, v45
	s_waitcnt lgkmcnt(9)
	v_mfma_f32_32x32x16_bf16 v[0:15], v[142:145], v[166:169], v[0:15]
	ds_read_b128 v[142:145], v170 offset:26784
	v_add_f32_e32 v108, v44, v108
	v_exp_f32_e32 v46, v46
	v_add_f32_e32 v108, v45, v108
	v_cvt_pk_bf16_f32 v160, v44, v45
	s_waitcnt lgkmcnt(9)
	v_mfma_f32_32x32x16_bf16 v[16:31], v[150:153], v[166:169], v[16:31]
	ds_read_b128 v[150:153], v170 offset:35488
	v_exp_f32_e32 v47, v47
	v_add_f32_e32 v108, v46, v108
	v_add_f32_e32 v108, v47, v108
	v_cvt_pk_bf16_f32 v161, v46, v47
	s_waitcnt lgkmcnt(3)
	v_mfma_f32_32x32x16_bf16 v[0:15], v[138:141], v[154:157], v[0:15]
	ds_read_b128 v[138:141], v170 offset:26816
	v_exp_f32_e32 v172, v172
	v_exp_f32_e32 v173, v173
	v_add_f32_e32 v108, v172, v108
	v_exp_f32_e32 v174, v174
	v_add_u32_e32 v188, s29, v104
	s_waitcnt vmcnt(4)
	ds_write_b128 v188, v[84:87]
	s_waitcnt lgkmcnt(4)
	v_mfma_f32_32x32x16_bf16 v[16:31], v[146:149], v[154:157], v[16:31]
	ds_read_b128 v[146:149], v170 offset:35520
	v_add_f32_e32 v108, v173, v108
	v_cvt_pk_bf16_f32 v162, v172, v173
	v_exp_f32_e32 v175, v175
	v_add_f32_e32 v108, v174, v108
	v_add_u32_e32 v189, s29, v105
	s_waitcnt vmcnt(3)
	ds_write_b128 v189, v[72:75]
	s_waitcnt lgkmcnt(5)
	v_mfma_f32_32x32x16_bf16 v[0:15], v[142:145], v[158:161], v[0:15]
	ds_read_b128 v[142:145], v170 offset:26848
	v_exp_f32_e32 v176, v176
	v_add_f32_e32 v108, v175, v108
	v_cvt_pk_bf16_f32 v163, v174, v175
	v_exp_f32_e32 v177, v177
	v_add_u32_e32 v190, s29, v106
	s_waitcnt vmcnt(2)
	ds_write_b128 v190, v[76:79]
	s_waitcnt lgkmcnt(6)
; #define KLOAD(kf_, base)                                                                       \
;   { _Pragma("unroll") for (int ks = 0; ks < NKS; ks++) kf_[ks] = *(const bf16x8*)((base) + kfo + ks * 32); }
; #define VLOAD(vf_, base)                                                                       \
;   { _Pragma("unroll") for (int q = 0; q < 4; q++) vf_[q] = *(const bf16x8*)((base) + vfo + (q >> 1) * 32 * VROW + (q & 1) * 32); }
; #define QKM(dst, kf_)                                                                          \
;   {                                                                                            \
;     _Pragma("unroll") for (int i = 0; i < 16; i++) dst[i] = 0.f;                               \
;     _Pragma("unroll") for (int ks = 0; ks < NKS; ks++) dst = MFMA(kf_[ks], qf[ks], dst);       \
;   }
; #define SB() __builtin_amdgcn_sched_barrier(0)
; template <int DK>
; DI void attn_core(const bf16x8 (&qf)[DK / 16], const short* Kg, const short* VTg, size_t ldvt, int ntiles, char* smem,
;                   f32x16 (&O)[2], float& lsum) {
;     ...
;     KLOAD(kf, nxt);
;     VLOAD(vf, cur + 128);
;     SB();
;     SOFTMAX(Sn, qa, qb, l0);
;     SB();
;     QKM(Sc, kf);
;     PVM(vf, pa, pb);
;     SB();
;     VLOAD(vf, cur + 192);
;     PVM(vf, qa, qb);
;     ASTORE(sw);
;     __syncthreads();
;     const int tmp = sc; sc = sn; sn = sw; sw = tmp;
	v_mfma_f32_32x32x16_bf16 v[16:31], v[150:153], v[158:161], v[16:31]
	ds_read_b128 v[150:153], v170 offset:35552
	v_add_f32_e32 v108, v176, v108
	v_exp_f32_e32 v178, v178
	v_add_f32_e32 v108, v177, v108
	v_cvt_pk_bf16_f32 v164, v176, v177
	v_add_u32_e32 v191, s29, v100
	s_waitcnt vmcnt(1)
	ds_write_b128 v191, v[80:83] offset:26624
	s_waitcnt lgkmcnt(14)
	v_mfma_f32_32x32x16_bf16 v[32:47], v[110:113], v[48:51], 0
	ds_read_b128 v[110:113], v109 offset:6656
	v_exp_f32_e32 v179, v179
	v_add_f32_e32 v108, v178, v108
	v_exp_f32_e32 v180, v180
	v_add_f32_e32 v108, v179, v108
	s_waitcnt vmcnt(0)
	ds_write_b128 v191, v[88:91] offset:35328
	s_waitcnt lgkmcnt(14)
	v_mfma_f32_32x32x16_bf16 v[32:47], v[114:117], v[52:55], v[32:47]
	ds_read_b128 v[114:117], v109 offset:6688
	v_cvt_pk_bf16_f32 v165, v178, v179
	v_exp_f32_e32 v181, v181
	v_add_f32_e32 v108, v180, v108
	v_exp_f32_e32 v182, v182
	s_waitcnt lgkmcnt(14)
	v_mfma_f32_32x32x16_bf16 v[32:47], v[118:121], v[56:59], v[32:47]
	ds_read_b128 v[118:121], v109 offset:6720
	v_add_f32_e32 v108, v181, v108
	v_cvt_pk_bf16_f32 v166, v180, v181
	v_exp_f32_e32 v183, v183
	v_add_f32_e32 v108, v182, v108
	s_waitcnt lgkmcnt(14)
	v_mfma_f32_32x32x16_bf16 v[32:47], v[122:125], v[60:63], v[32:47]
	ds_read_b128 v[122:125], v109 offset:6752
	v_exp_f32_e32 v184, v184
	v_add_f32_e32 v108, v183, v108
	v_cvt_pk_bf16_f32 v167, v182, v183
	v_exp_f32_e32 v185, v185
	s_waitcnt lgkmcnt(14)
	v_mfma_f32_32x32x16_bf16 v[32:47], v[130:133], v[64:67], v[32:47]
	ds_read_b128 v[130:133], v109 offset:6784
	v_add_f32_e32 v108, v184, v108
	v_exp_f32_e32 v186, v186
	v_add_f32_e32 v108, v185, v108
	v_cvt_pk_bf16_f32 v168, v184, v185
	s_waitcnt lgkmcnt(14)
	v_mfma_f32_32x32x16_bf16 v[32:47], v[134:137], v[68:71], v[32:47]
	ds_read_b128 v[134:137], v109 offset:6816
	v_exp_f32_e32 v187, v187
	v_add_f32_e32 v108, v186, v108
	v_add_f32_e32 v108, v187, v108
	v_cvt_pk_bf16_f32 v169, v186, v187
	s_add_i32 s21, s21, 1
	s_mov_b32 s30, s28
	s_mov_b32 s28, s22
	s_mov_b32 s22, s23
	s_mov_b32 s23, s30
	s_min_u32 s29, s21, 0x7d
	s_add_i32 s29, s29, 2
	s_mul_i32 s34, s29, 0x6000
	s_add_u32 s34, s8, s34
	s_addc_u32 s35, s9, 0
	s_lshl_b32 s30, s29, 8
	s_mul_i32 s29, s28, 0xac00
	v_add_u32_e32 v128, s29, v107
	v_add_u32_e32 v170, s29, v101
	s_mul_i32 s29, s22, 0xac00
	v_add_u32_e32 v109, s29, v107
	s_cmpk_lg_i32 s21, 0x80
	s_waitcnt lgkmcnt(5)
	s_barrier
	s_cbranch_scc1 .Lmla_prompt_loop
	s_waitcnt lgkmcnt(0)
	s_barrier
; DI int my_tid() { int t = threadIdx.x; asm volatile("" : "+v"(t)); return t; }
; DI float bf_lo(unsigned u) { return __uint_as_float(u << 16); }
; DI float bf_hi(unsigned u) { return __uint_as_float(u & 0xffff0000u); }
; DI void attn_store(const f32x16 (&O)[2], float lsum, int tok, int col0, const short* gate, short* o, char* smem) {
;   const int tid = my_tid(), lane = tid & 63, w = tid >> 6, r = lane & 31, h = lane >> 5;
;   float l = lsum + __shfl_xor(lsum, 32);
;   float inv = __builtin_amdgcn_rcpf(l);
;   float* pw = (float*)(smem + w * (32 * 68 * 4));
;   const int tokw = tok - r;
;   const int ch = lane & 7;
;   u32x4 gpre[4];
; #pragma unroll
;   for (int j = 0; j < 4; j++) gpre[j] = *(const u32x4*)(gate + (size_t)(tokw + j * 8 + (lane >> 3)) * 1024 + col0 + ch * 8);
; #pragma unroll
;   for (int dt = 0; dt < 2; dt++)
; #pragma unroll
;     for (int q = 0; q < 4; q++) {
;       f32x4 t = {O[dt][q * 4 + 0] * inv, O[dt][q * 4 + 1] * inv, O[dt][q * 4 + 2] * inv, O[dt][q * 4 + 3] * inv};
;       *(f32x4*)(pw + r * 68 + dt * 32 + 8 * q + 4 * h) = t;
;     }
;   asm volatile("s_waitcnt lgkmcnt(0)" ::: "memory");
; #pragma unroll
;   for (int j = 0; j < 4; j++) {
;     const int row = j * 8 + (lane >> 3);
;     const size_t g = (size_t)(tokw + row) * 1024 + col0 + ch * 8;
;     const u32x4 gv = gpre[j];
;     const f32x4 a = *(const f32x4*)(pw + row * 68 + ch * 8), c = *(const f32x4*)(pw + row * 68 + ch * 8 + 4);
;     u32x4 ov;
;     ov[0] = pack_bf16(a[0] * bf_lo(gv[0]), a[1] * bf_hi(gv[0]));
;     ov[1] = pack_bf16(a[2] * bf_lo(gv[1]), a[3] * bf_hi(gv[1]));
;     ov[2] = pack_bf16(c[0] * bf_lo(gv[2]), c[1] * bf_hi(gv[2]));
;     ov[3] = pack_bf16(c[2] * bf_lo(gv[3]), c[3] * bf_hi(gv[3]));
;     __builtin_nontemporal_store(ov, (u32x4*)(o + g));
;   }
;   __syncthreads();
; }
	v_mfma_f32_32x32x16_bf16 v[0:15], v[138:141], v[162:165], v[0:15]
	v_mfma_f32_32x32x16_bf16 v[16:31], v[146:149], v[162:165], v[16:31]
	v_mfma_f32_32x32x16_bf16 v[0:15], v[142:145], v[166:169], v[0:15]
	v_mfma_f32_32x32x16_bf16 v[16:31], v[150:153], v[166:169], v[16:31]
	s_nop 10
	ds_bpermute_b32 v33, v103, v108
	s_lshl_b32 s8, s16, 6
	v_mov_b32_e32 v57, v196
	s_ashr_i32 s9, s8, 31
	v_lshrrev_b32_e32 v32, 6, v57
	v_and_b32_e32 v58, 31, v57
	s_waitcnt lgkmcnt(0)
	v_add_f32_e32 v56, v108, v33
	v_mul_lo_u32 v59, v32, s38
	v_sub_u32_e32 v32, v102, v58
	v_bfe_u32 v60, v57, 3, 3
	s_lshl_b64 s[8:9], s[8:9], 1
	v_lshlrev_b32_e32 v33, 3, v57
	v_add_u32_e32 v32, v60, v32
	s_add_u32 s22, s14, s8
	v_and_b32_e32 v61, 56, v33
	s_addc_u32 s23, s15, s9
	v_lshlrev_b32_e32 v128, 1, v61
	v_ashrrev_i32_e32 v33, 31, v32
	v_lshl_add_u64 v[34:35], s[22:23], 0, v[128:129]
	v_lshlrev_b64 v[54:55], 11, v[32:33]
	v_lshl_add_u64 v[36:37], v[34:35], 0, v[54:55]
	global_load_dwordx4 v[44:47], v[36:37], off
	v_add_u32_e32 v36, 8, v32
	v_ashrrev_i32_e32 v37, 31, v36
	v_lshlrev_b64 v[52:53], 11, v[36:37]
	v_lshl_add_u64 v[36:37], v[34:35], 0, v[52:53]
	global_load_dwordx4 v[40:43], v[36:37], off
	v_add_u32_e32 v36, 16, v32
	v_ashrrev_i32_e32 v37, 31, v36
	v_lshlrev_b64 v[50:51], 11, v[36:37]
	v_lshl_add_u64 v[36:37], v[34:35], 0, v[50:51]
	global_load_dwordx4 v[36:39], v[36:37], off
	v_add_u32_e32 v32, 24, v32
	v_ashrrev_i32_e32 v33, 31, v32
	v_lshlrev_b64 v[48:49], 11, v[32:33]
	v_lshl_add_u64 v[32:33], v[34:35], 0, v[48:49]
	global_load_dwordx4 v[32:35], v[32:33], off
	v_rcp_f32_e32 v56, v56
	v_lshrrev_b32_e32 v57, 1, v57
	v_mul_u32_u24_e32 v58, 0x110, v58
	v_and_b32_e32 v57, 16, v57
	v_add3_u32 v57, v59, v58, v57
	v_pk_mul_f32 v[0:1], v[0:1], v[56:57] op_sel_hi:[1,0]
	v_pk_mul_f32 v[2:3], v[2:3], v[56:57] op_sel_hi:[1,0]
	ds_write_b128 v57, v[0:3]
	v_pk_mul_f32 v[0:1], v[4:5], v[56:57] op_sel_hi:[1,0]
	v_pk_mul_f32 v[2:3], v[6:7], v[56:57] op_sel_hi:[1,0]
	ds_write_b128 v57, v[0:3] offset:32
	v_pk_mul_f32 v[0:1], v[8:9], v[56:57] op_sel_hi:[1,0]
	v_pk_mul_f32 v[2:3], v[10:11], v[56:57] op_sel_hi:[1,0]
	ds_write_b128 v57, v[0:3] offset:64
	v_pk_mul_f32 v[0:1], v[12:13], v[56:57] op_sel_hi:[1,0]
	v_pk_mul_f32 v[2:3], v[14:15], v[56:57] op_sel_hi:[1,0]
	ds_write_b128 v57, v[0:3] offset:96
	v_pk_mul_f32 v[0:1], v[16:17], v[56:57] op_sel_hi:[1,0]
	v_pk_mul_f32 v[2:3], v[18:19], v[56:57] op_sel_hi:[1,0]
	ds_write_b128 v57, v[0:3] offset:128
	v_pk_mul_f32 v[0:1], v[20:21], v[56:57] op_sel_hi:[1,0]
	v_pk_mul_f32 v[2:3], v[22:23], v[56:57] op_sel_hi:[1,0]
	ds_write_b128 v57, v[0:3] offset:160
	v_pk_mul_f32 v[0:1], v[24:25], v[56:57] op_sel_hi:[1,0]
	v_pk_mul_f32 v[2:3], v[26:27], v[56:57] op_sel_hi:[1,0]
	ds_write_b128 v57, v[0:3] offset:192
	v_pk_mul_f32 v[0:1], v[28:29], v[56:57] op_sel_hi:[1,0]
	v_pk_mul_f32 v[2:3], v[30:31], v[56:57] op_sel_hi:[1,0]
	ds_write_b128 v57, v[0:3] offset:224
	v_lshl_or_b32 v2, v61, 2, v59
	s_movk_i32 s36, 0x110
	s_waitcnt lgkmcnt(0)
	v_mad_u32_u24 v12, v60, s36, v2
	ds_read_b128 v[2:5], v12
	ds_read_b128 v[6:9], v12 offset:16
	s_add_u32 s8, s18, s8
	s_addc_u32 s9, s19, s9
	v_lshl_add_u64 v[0:1], s[8:9], 0, v[128:129]
	v_readlane_b32 s8, v226, 12
	s_add_i32 s20, s20, s8
	s_cmpk_gt_i32 s20, 0x5f
	s_waitcnt vmcnt(3)
	v_lshlrev_b32_e32 v10, 16, v44
	v_and_b32_e32 v11, 0xffff0000, v44
	s_waitcnt lgkmcnt(1)
	v_pk_mul_f32 v[2:3], v[2:3], v[10:11]
	v_lshlrev_b32_e32 v10, 16, v45
	v_and_b32_e32 v11, 0xffff0000, v45
	v_pk_mul_f32 v[4:5], v[4:5], v[10:11]
	v_cvt_pk_bf16_f32 v2, v2, v3
	v_cvt_pk_bf16_f32 v3, v4, v5
	v_lshlrev_b32_e32 v4, 16, v46
	v_and_b32_e32 v5, 0xffff0000, v46
	s_waitcnt lgkmcnt(0)
	v_pk_mul_f32 v[4:5], v[6:7], v[4:5]
	v_lshlrev_b32_e32 v6, 16, v47
	v_and_b32_e32 v7, 0xffff0000, v47
	v_pk_mul_f32 v[6:7], v[8:9], v[6:7]
	v_cvt_pk_bf16_f32 v4, v4, v5
	v_cvt_pk_bf16_f32 v5, v6, v7
	v_lshl_add_u64 v[6:7], v[0:1], 0, v[54:55]
	global_store_dwordx4 v[6:7], v[2:5], off nt
	ds_read_b128 v[2:5], v12 offset:2176
	ds_read_b128 v[6:9], v12 offset:2192
	s_waitcnt vmcnt(3)
	v_lshlrev_b32_e32 v10, 16, v40
	v_and_b32_e32 v11, 0xffff0000, v40
	s_waitcnt lgkmcnt(1)
	v_pk_mul_f32 v[2:3], v[2:3], v[10:11]
	v_lshlrev_b32_e32 v10, 16, v41
	v_and_b32_e32 v11, 0xffff0000, v41
	v_pk_mul_f32 v[4:5], v[4:5], v[10:11]
	v_cvt_pk_bf16_f32 v2, v2, v3
	v_cvt_pk_bf16_f32 v3, v4, v5
	v_lshlrev_b32_e32 v4, 16, v42
	v_and_b32_e32 v5, 0xffff0000, v42
	s_waitcnt lgkmcnt(0)
	v_pk_mul_f32 v[4:5], v[6:7], v[4:5]
	v_lshlrev_b32_e32 v6, 16, v43
	v_and_b32_e32 v7, 0xffff0000, v43
	v_pk_mul_f32 v[6:7], v[8:9], v[6:7]
	v_cvt_pk_bf16_f32 v4, v4, v5
	v_cvt_pk_bf16_f32 v5, v6, v7
	v_lshl_add_u64 v[6:7], v[0:1], 0, v[52:53]
	global_store_dwordx4 v[6:7], v[2:5], off nt
	ds_read_b128 v[2:5], v12 offset:4352
	ds_read_b128 v[6:9], v12 offset:4368
	s_waitcnt vmcnt(3)
	v_lshlrev_b32_e32 v10, 16, v36
	v_and_b32_e32 v11, 0xffff0000, v36
	s_waitcnt lgkmcnt(1)
	v_pk_mul_f32 v[2:3], v[2:3], v[10:11]
	v_lshlrev_b32_e32 v10, 16, v37
	v_and_b32_e32 v11, 0xffff0000, v37
	v_pk_mul_f32 v[4:5], v[4:5], v[10:11]
	v_cvt_pk_bf16_f32 v2, v2, v3
	v_cvt_pk_bf16_f32 v3, v4, v5
	v_lshlrev_b32_e32 v4, 16, v38
	v_and_b32_e32 v5, 0xffff0000, v38
	s_waitcnt lgkmcnt(0)
	v_pk_mul_f32 v[4:5], v[6:7], v[4:5]
	v_lshlrev_b32_e32 v6, 16, v39
	v_and_b32_e32 v7, 0xffff0000, v39
	v_pk_mul_f32 v[6:7], v[8:9], v[6:7]
	v_cvt_pk_bf16_f32 v4, v4, v5
	v_cvt_pk_bf16_f32 v5, v6, v7
	v_lshl_add_u64 v[6:7], v[0:1], 0, v[50:51]
	global_store_dwordx4 v[6:7], v[2:5], off nt
	ds_read_b128 v[2:5], v12 offset:6528
	ds_read_b128 v[6:9], v12 offset:6544
	s_waitcnt vmcnt(3)
	v_lshlrev_b32_e32 v10, 16, v32
	v_and_b32_e32 v11, 0xffff0000, v32
	v_lshl_add_u64 v[0:1], v[0:1], 0, v[48:49]
	s_waitcnt lgkmcnt(1)
	v_pk_mul_f32 v[2:3], v[2:3], v[10:11]
	v_lshlrev_b32_e32 v10, 16, v33
	v_and_b32_e32 v11, 0xffff0000, v33
	v_pk_mul_f32 v[4:5], v[4:5], v[10:11]
	v_cvt_pk_bf16_f32 v2, v2, v3
	v_cvt_pk_bf16_f32 v3, v4, v5
	v_lshlrev_b32_e32 v4, 16, v34
	v_and_b32_e32 v5, 0xffff0000, v34
	s_waitcnt lgkmcnt(0)
	v_pk_mul_f32 v[4:5], v[6:7], v[4:5]
	v_lshlrev_b32_e32 v6, 16, v35
	v_and_b32_e32 v7, 0xffff0000, v35
	v_pk_mul_f32 v[6:7], v[8:9], v[6:7]
	v_cvt_pk_bf16_f32 v4, v4, v5
	v_cvt_pk_bf16_f32 v5, v6, v7
	global_store_dwordx4 v[0:1], v[2:5], off nt
	s_barrier
	s_cbranch_scc0 .LBB0_165

; DI int my_tid() { int t = threadIdx.x; asm volatile("" : "+v"(t)); return t; }
; DI float bf_lo(unsigned u) { return __uint_as_float(u << 16); }
; DI float bf_hi(unsigned u) { return __uint_as_float(u & 0xffff0000u); }
; DI float rsqrt_f(float x) { return __builtin_amdgcn_rsqf(x); }
; DI void rope_cs(int pos, int i, float& c, float& s) {
;   double t = (double)pos * ROPE_TURNS[i];
;   t -= floor(t);
;   float fr = (float)t;
;   s = __builtin_amdgcn_sinf(fr);
;   c = __builtin_amdgcn_cosf(fr);
; }
; DI void mla_item(PRef p, int j, int seq, int head, int qb, char* smem) {
;   const int tid = my_tid(), lane = tid & 63, w = tid >> 6, r = lane & 31, h = lane >> 5;
;   const int s0 = seq == 0 ? 0 : TP + (seq - 1) * SS;
;   const int S = seq == 0 ? TP : SS;
;   const int pos = qb * 256 + w * 32 + r;
;   const int tok = s0 + pos;
;   const short* Q = (const short*)(p.ws + OFF_Q);
;   const float* gq = p.in[10] + j * 96;
;   float qv[6][8];
;   float ss = 0.f;
; #pragma unroll
;   for (int ks = 0; ks < 6; ks++) {
;     u32x4 t = *(const u32x4*)(Q + (size_t)tok * 1152 + head * 96 + ks * 16 + 8 * h);
; #pragma unroll
;     for (int e = 0; e < 4; e++) {
;       qv[ks][2 * e] = bf_lo(t[e]);
;       qv[ks][2 * e + 1] = bf_hi(t[e]);
;     }
; #pragma unroll
;     for (int e = 0; e < 8; e++) ss += qv[ks][e] * qv[ks][e];
;   }
;   ss += __shfl_xor(ss, 32);
;   const float f = rsqrt_f(ss * (1.f / 96.f) + EPS);
;   const float sc = 0.10206207261596575f * LOG2E;
; #pragma unroll
;   for (int ks = 0; ks < 6; ks++)
; #pragma unroll
;     for (int e = 0; e < 8; e++) qv[ks][e] *= f * gq[ks * 16 + 8 * h + e];
; #pragma unroll
;   for (int e = 0; e < 8; e++) {
;     float cs, sn;
;     rope_cs(pos, 8 * h + e, cs, sn);
.LBB0_170:
	s_ashr_i32 s8, s22, 1
	s_and_b32 s8, s8, -8
	s_or_b32 s14, s8, s52
	s_mul_hi_i32 s8, s14, 0x2aaaaaab
	s_lshr_b32 s9, s8, 31
	s_ashr_i32 s8, s8, 1
	s_add_i32 s15, s8, s9
	v_add_co_u32_e64 v0, s[8:9], s15, 1
	s_mul_i32 s15, s15, 12
	s_sub_i32 s16, s14, s15
	v_readfirstlane_b32 s14, v0
	s_lshl_b32 s14, s14, 12
	s_add_i32 s23, s14, 0x3000
	s_and_b64 s[14:15], s[8:9], exec
	v_mov_b32_e32 v6, v196
	s_cselect_b32 s14, 0, s23
	s_getpc_b64 s[28:29]
	s_add_u32 s28, s28, _ZL10ROPE_TURNS@rel32@lo+4
	s_addc_u32 s29, s29, _ZL10ROPE_TURNS@rel32@hi+12
	s_lshl_b32 s15, s22, 8
	v_lshrrev_b32_e32 v0, 2, v6
	v_ashrrev_i32_e32 v8, 1, v6
	v_and_b32_e32 v7, 8, v0
	v_and_b32_e32 v8, 0xffffffe0, v8
	s_and_b32 s15, s15, 0xf00
	v_lshlrev_b32_e32 v0, 3, v7
	v_add_u32_e32 v8, s15, v8
	global_load_dwordx4 v[30:33], v0, s[28:29]
	global_load_dwordx4 v[34:37], v0, s[28:29] offset:16
	global_load_dwordx4 v[38:41], v0, s[28:29] offset:32
	global_load_dwordx4 v[2:5], v0, s[28:29] offset:48
	v_and_or_b32 v6, v6, 31, v8
	v_mov_b64_e32 v[0:1], s[4:5]
	s_mul_i32 s28, s16, 0x60
	v_add_u32_e32 v102, s14, v6
	s_movk_i32 s15, 0x900
	s_ashr_i32 s29, s28, 31
	v_mad_i64_i32 v[0:1], s[34:35], v102, s15, v[0:1]
	s_waitcnt vmcnt(11)
	v_lshlrev_b32_e32 v128, 1, v7
	v_lshl_add_u64 v[0:1], s[28:29], 1, v[0:1]
	v_lshl_add_u64 v[0:1], v[0:1], 0, v[128:129]
	global_load_dwordx4 v[26:29], v[0:1], off offset:128
	global_load_dwordx4 v[22:25], v[0:1], off offset:160
	global_load_dwordx4 v[18:21], v[0:1], off offset:96
	v_and_b32_e32 v9, 64, v200
	v_xor_b32_e32 v8, 32, v200
	v_add_u32_e32 v9, 64, v9
	v_cmp_lt_i32_e32 vcc, v8, v9
	v_lshlrev_b32_e32 v128, 2, v7
	v_cvt_f64_i32_e32 v[42:43], v6
	v_cndmask_b32_e32 v8, v200, v8, vcc
	v_lshlrev_b32_e32 v103, 2, v8
	global_load_dwordx4 v[6:9], v[0:1], off
	global_load_dwordx4 v[10:13], v[0:1], off offset:32
	global_load_dwordx4 v[14:17], v[0:1], off offset:64
	s_and_b64 s[8:9], s[8:9], exec
	s_cselect_b32 s29, 0x80, 32
	s_mul_i32 s9, s16, 0x14000
	s_ashr_i32 s15, s14, 31
	s_mul_hi_i32 s8, s16, 0x14000
	s_add_u32 s9, s9, s14
	s_addc_u32 s8, s8, s15
	s_mulk_i32 s8, 0xc0
	s_mul_hi_u32 s30, s9, 0xc0
	s_add_i32 s30, s30, s8
	s_mulk_i32 s9, 0xc0
	s_add_u32 s8, s10, s9
	s_addc_u32 s9, s11, s30
	s_mul_i32 s35, s16, 0xa00000
	s_mul_hi_i32 s30, s16, 0xa00000
	s_add_u32 s35, s12, s35
	s_addc_u32 s30, s13, s30
	s_lshl_b64 s[14:15], s[14:15], 1
	s_add_u32 s14, s35, s14
	s_addc_u32 s15, s30, s15
	s_mov_b32 s39, 0x500000
	s_mov_b32 s30, 0x3e16c740
	s_mov_b32 s34, 1
	s_mov_b32 s23, 0
	s_mov_b32 s28, 2
	s_waitcnt vmcnt(9)
	v_mul_f64 v[0:1], v[30:31], v[42:43]
	v_mul_f64 v[44:45], v[32:33], v[42:43]
	v_floor_f64_e32 v[0:1], v[0:1]
	s_waitcnt vmcnt(6)
	v_mul_f64 v[54:55], v[2:3], v[42:43]
	v_floor_f64_e32 v[44:45], v[44:45]
	v_floor_f64_e32 v[54:55], v[54:55]
	v_fma_f64 v[0:1], v[30:31], v[42:43], -v[0:1]
	v_fma_f64 v[30:31], v[32:33], v[42:43], -v[44:45]
	v_fma_f64 v[2:3], v[2:3], v[42:43], -v[54:55]
	v_cvt_f32_f64_e32 v0, v[0:1]
	v_mul_f64 v[46:47], v[34:35], v[42:43]
	v_mul_f64 v[48:49], v[36:37], v[42:43]
	v_mul_f64 v[50:51], v[38:39], v[42:43]
	v_mul_f64 v[52:53], v[40:41], v[42:43]
	v_cvt_f32_f64_e32 v1, v[30:31]
	v_sin_f32_e32 v72, v0
	v_cos_f32_e32 v64, v0
	v_cvt_f32_f64_e32 v0, v[2:3]
	v_floor_f64_e32 v[46:47], v[46:47]
	v_floor_f64_e32 v[48:49], v[48:49]
	v_floor_f64_e32 v[50:51], v[50:51]
	v_floor_f64_e32 v[52:53], v[52:53]
	v_sin_f32_e32 v73, v1
	v_cos_f32_e32 v65, v1
	v_sin_f32_e32 v70, v0
	v_cos_f32_e32 v68, v0
	v_mul_f64 v[0:1], v[4:5], v[42:43]
	v_fma_f64 v[32:33], v[34:35], v[42:43], -v[46:47]
	v_fma_f64 v[34:35], v[36:37], v[42:43], -v[48:49]
	v_fma_f64 v[36:37], v[38:39], v[42:43], -v[50:51]
	v_fma_f64 v[38:39], v[40:41], v[42:43], -v[52:53]
	v_floor_f64_e32 v[44:45], v[0:1]
	global_load_dwordx4 v[0:3], v128, s[6:7] offset:256
	s_waitcnt vmcnt(4)
	v_lshlrev_b32_e32 v104, 16, v21
	v_and_b32_e32 v105, 0xffff0000, v21
	global_load_dwordx4 v[82:85], v128, s[6:7] offset:208
	global_load_dwordx4 v[86:89], v128, s[6:7] offset:192
	v_lshlrev_b32_e32 v108, 16, v20
	v_and_b32_e32 v109, 0xffff0000, v20
	v_lshlrev_b32_e32 v112, 16, v19
	v_and_b32_e32 v113, 0xffff0000, v19
	v_lshlrev_b32_e32 v116, 16, v18
	v_and_b32_e32 v117, 0xffff0000, v18
	global_load_dwordx4 v[18:21], v128, s[6:7] offset:144
	global_load_dwordx4 v[78:81], v128, s[6:7] offset:128
	global_load_dwordx4 v[60:63], v128, s[6:7] offset:80
	global_load_dwordx4 v[56:59], v128, s[6:7] offset:64
	global_load_dwordx4 v[50:53], v128, s[6:7]
	global_load_dwordx4 v[90:93], v128, s[6:7] offset:16
	s_waitcnt vmcnt(11)
	v_lshlrev_b32_e32 v156, 16, v6
	v_and_b32_e32 v157, 0xffff0000, v6
	v_lshlrev_b32_e32 v152, 16, v7
	v_and_b32_e32 v153, 0xffff0000, v7
	v_pk_mul_f32 v[6:7], v[156:157], v[156:157]
	v_pk_mul_f32 v[154:155], v[152:153], v[152:153]
	v_add_f32_e32 v6, v6, v7
	v_lshlrev_b32_e32 v150, 16, v8
	v_and_b32_e32 v151, 0xffff0000, v8
	v_add_f32_e32 v6, v154, v6
	v_lshlrev_b32_e32 v146, 16, v9
	v_and_b32_e32 v147, 0xffff0000, v9
	v_pk_mul_f32 v[8:9], v[150:151], v[150:151]
	v_add_f32_e32 v6, v155, v6
	v_add_f32_e32 v6, v8, v6
	v_pk_mul_f32 v[148:149], v[146:147], v[146:147]
	v_add_f32_e32 v6, v9, v6
	s_waitcnt vmcnt(10)
	v_lshlrev_b32_e32 v144, 16, v10
	v_and_b32_e32 v145, 0xffff0000, v10
	v_add_f32_e32 v6, v148, v6
	v_lshlrev_b32_e32 v140, 16, v11
	v_and_b32_e32 v141, 0xffff0000, v11
	v_pk_mul_f32 v[10:11], v[144:145], v[144:145]
	v_add_f32_e32 v6, v149, v6
	v_add_f32_e32 v6, v10, v6
	v_pk_mul_f32 v[142:143], v[140:141], v[140:141]
	v_add_f32_e32 v6, v11, v6
	v_lshlrev_b32_e32 v138, 16, v12
	v_and_b32_e32 v139, 0xffff0000, v12
	v_add_f32_e32 v6, v142, v6
	v_lshlrev_b32_e32 v134, 16, v13
	v_and_b32_e32 v135, 0xffff0000, v13
	v_pk_mul_f32 v[12:13], v[138:139], v[138:139]
	v_add_f32_e32 v6, v143, v6
	v_add_f32_e32 v6, v12, v6
	v_pk_mul_f32 v[136:137], v[134:135], v[134:135]
	v_add_f32_e32 v6, v13, v6
	s_waitcnt vmcnt(9)
; DI float bf_lo(unsigned u) { return __uint_as_float(u << 16); }
; DI float bf_hi(unsigned u) { return __uint_as_float(u & 0xffff0000u); }
; DI float rsqrt_f(float x) { return __builtin_amdgcn_rsqf(x); }
; template <int DK>
; DI void attn_core(const bf16x8 (&qf)[DK / 16], const short* Kg, const short* VTg, size_t ldvt, int ntiles, char* smem,
;                   f32x16 (&O)[2], float& lsum) {
;     ...
;   for (int i = 0; i < NKC; i++) { int c = tid + 512 * i; koff[i] = (c / KCH) * KROW + (c % KCH) * 16; }
;   const int vrow = tid >> 4, vcol = tid & 15;
;   const short* vg = VTg + (size_t)vrow * ldvt + vcol * 8;
;   const int voff = KT_BYTES + vrow * VROW + vcol * 16;
; #pragma unroll
;   for (int i = 0; i < 16; i++) { O[0][i] = 0.f; O[1][i] = 0.f; }
;   float l0 = 0.f;
; DI void mla_item(PRef p, int j, int seq, int head, int qb, char* smem) {
;     ...
; #pragma unroll
;   for (int ks = 0; ks < 6; ks++) {
;     u32x4 t = *(const u32x4*)(Q + (size_t)tok * 1152 + head * 96 + ks * 16 + 8 * h);
; #pragma unroll
;     for (int e = 0; e < 4; e++) {
;       qv[ks][2 * e] = bf_lo(t[e]);
;       qv[ks][2 * e + 1] = bf_hi(t[e]);
;     }
; #pragma unroll
;     for (int e = 0; e < 8; e++) ss += qv[ks][e] * qv[ks][e];
;   }
;   ss += __shfl_xor(ss, 32);
;   const float f = rsqrt_f(ss * (1.f / 96.f) + EPS);
;   const float sc = 0.10206207261596575f * LOG2E;
; #pragma unroll
;   for (int ks = 0; ks < 6; ks++)
; #pragma unroll
;     for (int e = 0; e < 8; e++) qv[ks][e] *= f * gq[ks * 16 + 8 * h + e];
; #pragma unroll
;   for (int e = 0; e < 8; e++) {
;     float cs, sn;
;     rope_cs(pos, 8 * h + e, cs, sn);
;     float x1 = qv[4][e], x2 = qv[5][e];
;     qv[4][e] = x1 * cs - x2 * sn;
;     qv[5][e] = x1 * sn + x2 * cs;
;   }
	v_lshlrev_b32_e32 v132, 16, v14
	v_and_b32_e32 v133, 0xffff0000, v14
	v_add_f32_e32 v6, v136, v6
	v_lshlrev_b32_e32 v126, 16, v15
	v_and_b32_e32 v127, 0xffff0000, v15
	v_pk_mul_f32 v[14:15], v[132:133], v[132:133]
	v_add_f32_e32 v6, v137, v6
	v_add_f32_e32 v6, v14, v6
	v_pk_mul_f32 v[130:131], v[126:127], v[126:127]
	v_add_f32_e32 v6, v15, v6
	v_lshlrev_b32_e32 v124, 16, v16
	v_and_b32_e32 v125, 0xffff0000, v16
	v_add_f32_e32 v6, v130, v6
	v_lshlrev_b32_e32 v120, 16, v17
	v_and_b32_e32 v121, 0xffff0000, v17
	v_pk_mul_f32 v[16:17], v[124:125], v[124:125]
	v_add_f32_e32 v6, v131, v6
	v_add_f32_e32 v6, v16, v6
	v_pk_mul_f32 v[122:123], v[120:121], v[120:121]
	v_add_f32_e32 v6, v17, v6
	v_add_f32_e32 v6, v122, v6
	v_pk_mul_f32 v[118:119], v[116:117], v[116:117]
	v_add_f32_e32 v6, v123, v6
	v_add_f32_e32 v6, v118, v6
	v_pk_mul_f32 v[114:115], v[112:113], v[112:113]
	v_add_f32_e32 v6, v119, v6
	v_add_f32_e32 v6, v114, v6
	v_pk_mul_f32 v[110:111], v[108:109], v[108:109]
	v_add_f32_e32 v6, v115, v6
	v_add_f32_e32 v6, v110, v6
	v_pk_mul_f32 v[106:107], v[104:105], v[104:105]
	v_add_f32_e32 v6, v111, v6
	v_lshlrev_b32_e32 v40, 16, v26
	v_and_b32_e32 v41, 0xffff0000, v26
	v_add_f32_e32 v6, v106, v6
	v_pk_mul_f32 v[100:101], v[40:41], v[40:41]
	v_add_f32_e32 v6, v107, v6
	v_cvt_f32_f64_e32 v30, v[32:33]
	v_cvt_f32_f64_e32 v33, v[38:39]
	v_lshlrev_b32_e32 v38, 16, v27
	v_and_b32_e32 v39, 0xffff0000, v27
	v_add_f32_e32 v6, v100, v6
	v_pk_mul_f32 v[96:97], v[38:39], v[38:39]
	v_add_f32_e32 v6, v101, v6
	v_cvt_f32_f64_e32 v32, v[36:37]
	v_lshlrev_b32_e32 v36, 16, v28
	v_and_b32_e32 v37, 0xffff0000, v28
	v_add_f32_e32 v6, v96, v6
	v_pk_mul_f32 v[54:55], v[36:37], v[36:37]
	v_add_f32_e32 v6, v97, v6
	v_cvt_f32_f64_e32 v31, v[34:35]
	v_lshlrev_b32_e32 v34, 16, v29
	v_and_b32_e32 v35, 0xffff0000, v29
	v_add_f32_e32 v6, v54, v6
	v_pk_mul_f32 v[46:47], v[34:35], v[34:35]
	v_add_f32_e32 v6, v55, v6
	v_lshlrev_b32_e32 v26, 16, v22
	v_and_b32_e32 v27, 0xffff0000, v22
	v_add_f32_e32 v6, v46, v6
	v_sin_f32_e32 v76, v30
	v_cos_f32_e32 v74, v30
	v_sin_f32_e32 v77, v31
	v_cos_f32_e32 v75, v31
	v_sin_f32_e32 v66, v32
	v_cos_f32_e32 v30, v32
	v_sin_f32_e32 v67, v33
	v_cos_f32_e32 v31, v33
	v_lshlrev_b32_e32 v32, 16, v25
	v_and_b32_e32 v33, 0xffff0000, v25
	v_lshlrev_b32_e32 v28, 16, v24
	v_and_b32_e32 v29, 0xffff0000, v24
	v_lshlrev_b32_e32 v24, 16, v23
	v_and_b32_e32 v25, 0xffff0000, v23
	v_pk_mul_f32 v[22:23], v[26:27], v[26:27]
	v_add_f32_e32 v6, v47, v6
	v_add_f32_e32 v6, v22, v6
	v_pk_mul_f32 v[98:99], v[24:25], v[24:25]
	v_add_f32_e32 v6, v23, v6
	v_add_f32_e32 v6, v98, v6
	v_pk_mul_f32 v[94:95], v[28:29], v[28:29]
	v_add_f32_e32 v6, v99, v6
	v_add_f32_e32 v6, v94, v6
	v_pk_mul_f32 v[48:49], v[32:33], v[32:33]
	v_add_f32_e32 v6, v95, v6
	v_add_f32_e32 v6, v48, v6
	v_add_f32_e32 v6, v49, v6
	ds_bpermute_b32 v7, v103, v6
	v_fma_f64 v[4:5], v[4:5], v[42:43], -v[44:45]
	v_cvt_f32_f64_e32 v4, v[4:5]
	v_sin_f32_e32 v71, v4
	v_cos_f32_e32 v69, v4
	s_waitcnt lgkmcnt(0)
	v_add_f32_e32 v4, v6, v7
	v_fmamk_f32 v4, v4, 0x3c2aaaab, v198
	v_rsq_f32_e32 v48, v4
	global_load_dwordx4 v[12:15], v128, s[6:7] offset:272
	global_load_dwordx4 v[4:7], v128, s[6:7] offset:336
	global_load_dwordx4 v[8:11], v128, s[6:7] offset:320
	s_waitcnt vmcnt(4)
	v_pk_mul_f32 v[16:17], v[50:51], v[48:49] op_sel_hi:[1,0]
	s_nop 0
	v_pk_mul_f32 v[46:47], v[16:17], v[156:157]
	v_pk_mul_f32 v[16:17], v[52:53], v[48:49] op_sel_hi:[1,0]
	v_pk_mul_f32 v[0:1], v[0:1], v[48:49] op_sel_hi:[1,0]
	v_pk_mul_f32 v[50:51], v[16:17], v[152:153]
	s_waitcnt vmcnt(3)
	v_pk_mul_f32 v[16:17], v[90:91], v[48:49] op_sel_hi:[1,0]
	s_nop 0
	v_pk_mul_f32 v[52:53], v[16:17], v[150:151]
	v_pk_mul_f32 v[16:17], v[92:93], v[48:49] op_sel_hi:[1,0]
	v_mov_b32_e32 v150, v196
	v_pk_mul_f32 v[54:55], v[16:17], v[146:147]
	v_pk_mul_f32 v[16:17], v[56:57], v[48:49] op_sel_hi:[1,0]
	s_nop 0
	v_pk_mul_f32 v[56:57], v[16:17], v[144:145]
	v_pk_mul_f32 v[16:17], v[58:59], v[48:49] op_sel_hi:[1,0]
	v_ashrrev_i32_e32 v151, 4, v150
	v_pk_mul_f32 v[58:59], v[16:17], v[140:141]
	v_pk_mul_f32 v[16:17], v[60:61], v[48:49] op_sel_hi:[1,0]
	v_lshlrev_b32_e32 v92, 3, v150
	v_pk_mul_f32 v[60:61], v[16:17], v[138:139]
	v_pk_mul_f32 v[16:17], v[62:63], v[48:49] op_sel_hi:[1,0]
	v_add_u32_e32 v96, 0x2000, v92
	v_pk_mul_f32 v[62:63], v[16:17], v[134:135]
	v_pk_mul_f32 v[16:17], v[78:79], v[48:49] op_sel_hi:[1,0]
	v_ashrrev_i32_e32 v93, 31, v92
	v_pk_mul_f32 v[78:79], v[16:17], v[132:133]
	v_pk_mul_f32 v[16:17], v[80:81], v[48:49] op_sel_hi:[1,0]
	v_ashrrev_i32_e32 v97, 31, v96
	v_pk_mul_f32 v[80:81], v[16:17], v[126:127]
	v_pk_mul_f32 v[16:17], v[18:19], v[48:49] op_sel_hi:[1,0]
	v_pk_mul_f32 v[18:19], v[82:83], v[48:49] op_sel_hi:[1,0]
	v_mov_b64_e32 v[82:83], s[14:15]
	s_mov_b32 s14, 0x28000
	v_pk_mul_f32 v[22:23], v[16:17], v[124:125]
	v_pk_mul_f32 v[16:17], v[20:21], v[48:49] op_sel_hi:[1,0]
	v_mad_i64_i32 v[90:91], s[14:15], v151, s14, v[82:83]
	v_pk_mul_f32 v[42:43], v[16:17], v[120:121]
	v_pk_mul_f32 v[16:17], v[86:87], v[48:49] op_sel_hi:[1,0]
	s_add_u32 s14, s8, 0x6000
	v_pk_mul_f32 v[44:45], v[16:17], v[116:117]
	v_pk_mul_f32 v[16:17], v[88:89], v[48:49] op_sel_hi:[1,0]
	v_pk_mul_f32 v[20:21], v[84:85], v[48:49] op_sel_hi:[1,0]
	v_lshlrev_b32_e32 v49, 4, v150
	v_lshlrev_b64 v[100:101], 1, v[92:93]
	v_add_u32_e32 v94, 0x1000, v92
	v_lshlrev_b64 v[106:107], 1, v[96:97]
	s_addc_u32 s15, s9, 0
	v_and_b32_e32 v128, 0xf0, v49
	v_lshl_add_u64 v[82:83], s[8:9], 0, v[100:101]
	v_ashrrev_i32_e32 v95, 31, v94
	v_lshl_add_u64 v[98:99], s[8:9], 0, v[106:107]
	v_lshl_add_u64 v[100:101], s[14:15], 0, v[100:101]
	v_pk_mul_f32 v[18:19], v[18:19], v[108:109]
	v_pk_mul_f32 v[20:21], v[20:21], v[104:105]
	v_lshlrev_b64 v[104:105], 1, v[94:95]
	global_load_dwordx4 v[108:111], v[98:99], off
	global_load_dwordx4 v[120:123], v[100:101], off
	v_lshl_add_u64 v[98:99], v[90:91], 0, v[128:129]
	v_add_co_u32_e32 v90, vcc, s39, v98
	v_lshl_add_u64 v[100:101], s[14:15], 0, v[104:105]
	v_lshl_add_u64 v[86:87], s[8:9], 0, v[104:105]
	v_addc_co_u32_e32 v91, vcc, 0, v99, vcc
	global_load_dwordx4 v[124:127], v[100:101], off
	v_lshl_add_u64 v[100:101], s[14:15], 0, v[106:107]
	v_pk_mul_f32 v[16:17], v[16:17], v[112:113]
	global_load_dwordx4 v[82:85], v[82:83], off
	s_movk_i32 s14, 0xd0
	global_load_dwordx4 v[86:89], v[86:87], off
	s_nop 0
	global_load_dwordx4 v[112:115], v[98:99], off
	global_load_dwordx4 v[116:119], v[90:91], off
	global_load_dwordx4 v[130:133], v[100:101], off
	global_load_dwordx4 v[134:137], v[98:99], off offset:256
	global_load_dwordx4 v[138:141], v[90:91], off offset:256
	v_pk_mul_f32 v[90:91], v[0:1], v[40:41]
	v_pk_mul_f32 v[0:1], v[2:3], v[48:49] op_sel_hi:[1,0]
	v_mul_hi_i32 v3, v150, s41
	v_pk_mul_f32 v[142:143], v[0:1], v[38:39]
	s_waitcnt vmcnt(12)
; #define KLOAD(kf_, base)                                                                       \
;   { _Pragma("unroll") for (int ks = 0; ks < NKS; ks++) kf_[ks] = *(const bf16x8*)((base) + kfo + ks * 32); }
; #define QKM(dst, kf_)                                                                          \
;   {                                                                                            \
;     _Pragma("unroll") for (int i = 0; i < 16; i++) dst[i] = 0.f;                               \
;     _Pragma("unroll") for (int ks = 0; ks < NKS; ks++) dst = MFMA(kf_[ks], qf[ks], dst);       \
;   }
; template <int DK>
; DI void attn_core(const bf16x8 (&qf)[DK / 16], const short* Kg, const short* VTg, size_t ldvt, int ntiles, char* smem,
;                   f32x16 (&O)[2], float& lsum) {
;     ...
;   const int kfo = pr * KROW + h * 16;
;   const int vfo = KT_BYTES + r * VROW + h * 16;
;   AGLOAD(0);
;   ASTORE(0);
;   AGLOAD(ntiles > 1 ? 1 : 0);
;   ASTORE(1);
;   __syncthreads();
;   f32x16 Sc;
;   {
;     bf16x8 kf[NKS];
;     KLOAD(kf, smem);
;     QKM(Sc, kf);
;   }
; DI void mla_item(PRef p, int j, int seq, int head, int qb, char* smem) {
;     ...
; #pragma unroll
;   for (int ks = 0; ks < 6; ks++)
; #pragma unroll
;     for (int e = 0; e < 8; e++) qv[ks][e] *= f * gq[ks * 16 + 8 * h + e];
; #pragma unroll
;   for (int e = 0; e < 8; e++) {
;     float cs, sn;
;     rope_cs(pos, 8 * h + e, cs, sn);
;     float x1 = qv[4][e], x2 = qv[5][e];
;     qv[4][e] = x1 * cs - x2 * sn;
;     qv[5][e] = x1 * sn + x2 * cs;
;   }
;   bf16x8 qf[6];
; #pragma unroll
;   for (int ks = 0; ks < 6; ks++) {
;     u32x4 t;
; #pragma unroll
;     for (int e = 0; e < 4; e++) t[e] = pack_bf16(qv[ks][2 * e] * sc, qv[ks][2 * e + 1] * sc);
;     qf[ks] = __builtin_bit_cast(bf16x8, t);
;   }
	v_pk_mul_f32 v[0:1], v[12:13], v[48:49] op_sel_hi:[1,0]
	s_nop 0
	v_pk_mul_f32 v[12:13], v[0:1], v[36:37]
	v_pk_mul_f32 v[0:1], v[14:15], v[48:49] op_sel_hi:[1,0]
	s_nop 0
	v_pk_mul_f32 v[14:15], v[0:1], v[34:35]
	s_waitcnt vmcnt(10)
	v_pk_mul_f32 v[0:1], v[8:9], v[48:49] op_sel_hi:[1,0]
	s_nop 0
	v_pk_mul_f32 v[8:9], v[0:1], v[26:27]
	v_pk_mul_f32 v[0:1], v[10:11], v[48:49] op_sel_hi:[1,0]
	s_nop 0
	v_pk_mul_f32 v[10:11], v[0:1], v[24:25]
	v_pk_mul_f32 v[0:1], v[4:5], v[48:49] op_sel_hi:[1,0]
	v_pk_mul_f32 v[4:5], v[80:81], s[30:31] op_sel_hi:[1,0]
	v_pk_mul_f32 v[24:25], v[0:1], v[28:29]
	v_pk_mul_f32 v[0:1], v[6:7], v[48:49] op_sel_hi:[1,0]
	v_lshrrev_b32_e32 v6, 31, v3
	v_pk_mul_f32 v[26:27], v[0:1], v[32:33]
	v_pk_mul_f32 v[0:1], v[8:9], v[64:65]
	v_lshrrev_b32_e32 v3, 1, v3
	v_pk_fma_f32 v[28:29], v[90:91], v[72:73], v[0:1]
	v_pk_mul_f32 v[0:1], v[10:11], v[74:75]
	v_add_u32_e32 v3, v3, v6
	v_pk_fma_f32 v[144:145], v[142:143], v[76:77], v[0:1]
	v_pk_mul_f32 v[0:1], v[24:25], v[30:31]
	v_add_lshl_u32 v104, v3, v150, 4
	v_pk_fma_f32 v[146:147], v[12:13], v[66:67], v[0:1]
	v_pk_mul_f32 v[0:1], v[26:27], v[68:69]
	v_add_u32_e32 v3, 0x200, v150
	v_pk_fma_f32 v[148:149], v[14:15], v[70:71], v[0:1]
	v_pk_mul_f32 v[0:1], v[46:47], s[30:31] op_sel_hi:[1,0]
	v_mul_hi_i32 v6, v3, s41
	v_cvt_pk_bf16_f32 v48, v0, v1
	v_pk_mul_f32 v[0:1], v[50:51], s[30:31] op_sel_hi:[1,0]
	v_lshrrev_b32_e32 v7, 31, v6
	v_cvt_pk_bf16_f32 v49, v0, v1
	v_pk_mul_f32 v[0:1], v[52:53], s[30:31] op_sel_hi:[1,0]
	v_lshrrev_b32_e32 v6, 1, v6
	v_cvt_pk_bf16_f32 v50, v0, v1
	v_pk_mul_f32 v[0:1], v[54:55], s[30:31] op_sel_hi:[1,0]
	v_add_u32_e32 v6, v6, v7
	v_cvt_pk_bf16_f32 v51, v0, v1
	v_pk_mul_f32 v[0:1], v[56:57], s[30:31] op_sel_hi:[1,0]
	v_add_lshl_u32 v105, v6, v3, 4
	v_cvt_pk_bf16_f32 v52, v0, v1
	v_pk_mul_f32 v[0:1], v[58:59], s[30:31] op_sel_hi:[1,0]
	v_add_u32_e32 v3, 0x400, v150
	v_cvt_pk_bf16_f32 v53, v0, v1
	v_pk_mul_f32 v[0:1], v[60:61], s[30:31] op_sel_hi:[1,0]
	v_mul_hi_i32 v6, v3, s41
	v_cvt_pk_bf16_f32 v54, v0, v1
	v_pk_mul_f32 v[0:1], v[62:63], s[30:31] op_sel_hi:[1,0]
	v_lshrrev_b32_e32 v7, 31, v6
	v_cvt_pk_bf16_f32 v55, v0, v1
	v_pk_mul_f32 v[0:1], v[78:79], s[30:31] op_sel_hi:[1,0]
	v_lshrrev_b32_e32 v6, 1, v6
	v_cvt_pk_bf16_f32 v56, v0, v1
	v_lshlrev_b32_e32 v0, 1, v150
	v_lshrrev_b32_e32 v1, 1, v150
	v_add_u32_e32 v6, v6, v7
	v_and_b32_e32 v0, 8, v0
	v_and_b32_e32 v2, 4, v1
	v_add_lshl_u32 v106, v6, v3, 4
	v_and_b32_e32 v3, 19, v150
	v_and_b32_e32 v78, 16, v1
	v_or3_b32 v0, v3, v0, v2
	v_mad_u32_u24 v107, v0, s14, v78
	v_mad_u64_u32 v[100:101], s[14:15], v151, s36, v[128:129]
	v_add_u32_e32 v0, 0x6800, v100
	s_waitcnt vmcnt(6)
	ds_write_b128 v104, v[82:85]
	s_waitcnt vmcnt(5)
	ds_write_b128 v105, v[86:89]
	ds_write_b128 v106, v[108:111]
	s_waitcnt vmcnt(4)
	ds_write_b128 v100, v[112:115] offset:26624
	s_waitcnt vmcnt(3)
	ds_write_b128 v100, v[116:119] offset:35328
	ds_write_b128 v104, v[120:123] offset:44032
	ds_write_b128 v105, v[124:127] offset:44032
	s_waitcnt vmcnt(2)
	ds_write_b128 v106, v[130:133] offset:44032
	s_waitcnt vmcnt(1)
	ds_write_b128 v0, v[134:137] offset:44032
	s_waitcnt vmcnt(0)
	ds_write_b128 v0, v[138:141] offset:52736
	s_waitcnt lgkmcnt(0)
	s_barrier
	ds_read_b128 v[0:3], v107
	v_cvt_pk_bf16_f32 v57, v4, v5
	v_pk_mul_f32 v[4:5], v[22:23], s[30:31] op_sel_hi:[1,0]
	v_mov_b32_e32 v108, 0
	v_cvt_pk_bf16_f32 v58, v4, v5
	v_pk_mul_f32 v[4:5], v[42:43], s[30:31] op_sel_hi:[1,0]
	s_add_i32 s14, s29, -1
	v_cvt_pk_bf16_f32 v59, v4, v5
	v_pk_mul_f32 v[4:5], v[44:45], s[30:31] op_sel_hi:[1,0]
	s_mov_b32 s15, 0
	v_cvt_pk_bf16_f32 v60, v4, v5
	ds_read_b128 v[4:7], v107 offset:32
	s_waitcnt lgkmcnt(1)
	v_mfma_f32_32x32x16_bf16 v[32:47], v[0:3], v[48:51], 0
	v_mul_f32_e64 v0, v16, s30
	v_mul_f32_e64 v1, v17, s30
	v_mov_b32_e32 v16, 0
	v_cvt_pk_bf16_f32 v61, v0, v1
	v_mul_f32_e64 v0, v18, s30
	v_mul_f32_e64 v1, v19, s30
	v_mov_b32_e32 v17, v108
	v_cvt_pk_bf16_f32 v62, v0, v1
	v_pk_mul_f32 v[0:1], v[20:21], s[30:31] op_sel_hi:[1,0]
	s_waitcnt lgkmcnt(0)
	v_mfma_f32_32x32x16_bf16 v[32:47], v[4:7], v[52:55], v[32:47]
	v_cvt_pk_bf16_f32 v63, v0, v1
	ds_read_b128 v[0:3], v107 offset:64
	v_mul_f32_e64 v4, v8, v72
	v_mul_f32_e64 v5, v9, v73
	v_mov_b32_e32 v18, v108
	v_pk_fma_f32 v[4:5], v[90:91], v[64:65], v[4:5] neg_lo:[0,0,1] neg_hi:[0,0,1]
	v_mov_b32_e32 v19, v108
	v_pk_mul_f32 v[4:5], v[4:5], s[30:31] op_sel_hi:[1,0]
	v_mov_b32_e32 v20, v108
	v_cvt_pk_bf16_f32 v64, v4, v5
	v_pk_mul_f32 v[4:5], v[10:11], v[76:77]
	v_mov_b32_e32 v10, v108
	v_pk_fma_f32 v[8:9], v[142:143], v[74:75], v[4:5] neg_lo:[0,0,1] neg_hi:[0,0,1]
	ds_read_b128 v[4:7], v107 offset:96
	s_waitcnt lgkmcnt(1)
	v_mfma_f32_32x32x16_bf16 v[32:47], v[0:3], v[56:59], v[32:47]
	v_mul_f32_e64 v0, v8, s30
	v_mul_f32_e64 v1, v9, s30
	v_mov_b32_e32 v8, v108
	v_cvt_pk_bf16_f32 v65, v0, v1
	v_mul_f32_e64 v0, v24, v66
	v_mul_f32_e64 v1, v25, v67
	v_mov_b32_e32 v9, v108
	v_pk_fma_f32 v[0:1], v[12:13], v[30:31], v[0:1] neg_lo:[0,0,1] neg_hi:[0,0,1]
	v_mov_b32_e32 v11, v108
	v_pk_mul_f32 v[0:1], v[0:1], s[30:31] op_sel_hi:[1,0]
	s_waitcnt lgkmcnt(0)
	v_mfma_f32_32x32x16_bf16 v[32:47], v[4:7], v[60:63], v[32:47]
	v_cvt_pk_bf16_f32 v66, v0, v1
	ds_read_b128 v[0:3], v107 offset:128
	v_mul_f32_e64 v4, v26, v70
	v_mul_f32_e64 v5, v27, v71
	v_mov_b32_e32 v12, v108
	v_pk_fma_f32 v[4:5], v[14:15], v[68:69], v[4:5] neg_lo:[0,0,1] neg_hi:[0,0,1]
	v_mov_b32_e32 v13, v108
	v_pk_mul_f32 v[4:5], v[4:5], s[30:31] op_sel_hi:[1,0]
	v_mov_b32_e32 v14, v108
	v_cvt_pk_bf16_f32 v67, v4, v5
	v_pk_mul_f32 v[4:5], v[28:29], s[30:31] op_sel_hi:[1,0]
	v_mov_b32_e32 v15, v108
	v_cvt_pk_bf16_f32 v68, v4, v5
	ds_read_b128 v[4:7], v107 offset:160
	s_waitcnt lgkmcnt(1)
; #define KLOAD(kf_, base)                                                                       \
;   { _Pragma("unroll") for (int ks = 0; ks < NKS; ks++) kf_[ks] = *(const bf16x8*)((base) + kfo + ks * 32); }
; #define VLOAD(vf_, base)                                                                       \
;   { _Pragma("unroll") for (int q = 0; q < 4; q++) vf_[q] = *(const bf16x8*)((base) + vfo + (q >> 1) * 32 * VROW + (q & 1) * 32); }
; #define QKM(dst, kf_)                                                                          \
;   {                                                                                            \
;     _Pragma("unroll") for (int i = 0; i < 16; i++) dst[i] = 0.f;                               \
;     _Pragma("unroll") for (int ks = 0; ks < NKS; ks++) dst = MFMA(kf_[ks], qf[ks], dst);       \
;   }
; #define SB() __builtin_amdgcn_sched_barrier(0)
; template <int DK>
; DI void attn_core(const bf16x8 (&qf)[DK / 16], const short* Kg, const short* VTg, size_t ldvt, int ntiles, char* smem,
;                   f32x16 (&O)[2], float& lsum) {
;     ...
;   f32x16 Sc;
;   {
;     bf16x8 kf[NKS];
;     KLOAD(kf, smem);
;     QKM(Sc, kf);
;   }
;   int sc = 0, sn = 1, sw = 2;
;   for (int t = 0; t < ntiles; t++) {
;     const int tn = t + 2 < ntiles ? t + 2 : ntiles - 1;
;     AGLOAD(tn);
;     const char* cur = smem + sc * ST;
;     const char* nxt = smem + sn * ST;
;     f32x16 Sn;
;     bf16x8 pa, pb, qa, qb;
;     bf16x8 kf[NKS], vf[4];
;     KLOAD(kf, cur + 32 * KROW);
;     SB();
;     SOFTMAX(Sc, pa, pb, l0);
;     SB();
;     QKM(Sn, kf);
;     SB();
;     KLOAD(kf, cur + 64 * KROW);
;     VLOAD(vf, cur);
;     SB();
;     SOFTMAX(Sn, qa, qb, l0);
;     SB();
;     QKM(Sc, kf);
	v_mfma_f32_32x32x16_bf16 v[32:47], v[0:3], v[64:67], v[32:47]
	v_mul_f32_e64 v0, v144, s30
	v_mul_f32_e64 v1, v145, s30
	v_mov_b32_e32 v2, v108
	v_cvt_pk_bf16_f32 v69, v0, v1
	v_mul_f32_e64 v0, v146, s30
	v_mul_f32_e64 v1, v147, s30
	v_mov_b32_e32 v3, v108
	v_cvt_pk_bf16_f32 v70, v0, v1
	v_pk_mul_f32 v[0:1], v[148:149], s[30:31] op_sel_hi:[1,0]
	v_mov_b32_e32 v21, v108
	v_cvt_pk_bf16_f32 v71, v0, v1
	v_and_b32_e32 v0, 31, v150
	v_mad_u32_u24 v101, v0, s36, v78
	s_waitcnt lgkmcnt(0)
	v_mfma_f32_32x32x16_bf16 v[32:47], v[4:7], v[68:71], v[32:47]
	v_mov_b32_e32 v0, 0
	v_mov_b32_e32 v1, v108
	v_mov_b32_e32 v4, v108
	v_mov_b32_e32 v5, v108
	v_mov_b32_e32 v6, v108
	v_mov_b32_e32 v7, v108
	v_mov_b32_e32 v22, v108
	v_mov_b32_e32 v23, v108
	v_mov_b32_e32 v24, v108
	v_mov_b32_e32 v25, v108
	v_mov_b32_e32 v26, v108
	v_mov_b32_e32 v27, v108
	v_mov_b32_e32 v28, v108
	v_mov_b32_e32 v29, v108
	v_mov_b32_e32 v30, v108
	v_mov_b32_e32 v31, v108
	v_mov_b32_e32 v162, 0
	v_mov_b32_e32 v163, 0
	v_mov_b32_e32 v164, 0
	v_mov_b32_e32 v165, 0
	v_mov_b32_e32 v166, 0
	v_mov_b32_e32 v167, 0
	v_mov_b32_e32 v168, 0
	v_mov_b32_e32 v169, 0
	v_mov_b32_e32 v138, 0
	v_mov_b32_e32 v139, 0
	v_mov_b32_e32 v140, 0
	v_mov_b32_e32 v141, 0
	v_mov_b32_e32 v142, 0
	v_mov_b32_e32 v143, 0
	v_mov_b32_e32 v144, 0
	v_mov_b32_e32 v145, 0
	v_mov_b32_e32 v146, 0
	v_mov_b32_e32 v147, 0
	v_mov_b32_e32 v148, 0
	v_mov_b32_e32 v149, 0
	v_mov_b32_e32 v150, 0
	v_mov_b32_e32 v151, 0
	v_mov_b32_e32 v152, 0
	v_mov_b32_e32 v153, 0
	ds_read_b128 v[110:113], v107 offset:6656
	ds_read_b128 v[114:117], v107 offset:6688
	ds_read_b128 v[118:121], v107 offset:6720
	ds_read_b128 v[122:125], v107 offset:6752
	ds_read_b128 v[130:133], v107 offset:6784
	ds_read_b128 v[134:137], v107 offset:6816
	s_waitcnt lgkmcnt(0)
	s_add_i32 s35, s23, 2
	s_min_u32 s35, s35, s14
	s_mul_i32 s36, s35, 0x6000
	s_mul_hi_u32 s37, s35, 0x6000
	s_add_u32 s36, s8, s36
	s_addc_u32 s37, s9, s37
	s_lshl_b32 s30, s35, 8
	s_mul_i32 s35, s15, 0xac00
	v_add_u32_e32 v128, s35, v107
	v_add_u32_e32 v170, s35, v101
	s_mul_i32 s35, s34, 0xac00
	v_add_u32_e32 v109, s35, v107
.Lmla_sample_loop:
	s_waitcnt lgkmcnt(6)
	v_mfma_f32_32x32x16_bf16 v[172:187], v[110:113], v[48:51], 0
	ds_read_b128 v[110:113], v128 offset:13312
	v_exp_f32_e32 v32, v32
	v_exp_f32_e32 v33, v33
	v_add_f32_e32 v108, v32, v108
	v_exp_f32_e32 v34, v34
	v_lshl_add_u64 v[188:189], v[92:93], 1, s[36:37]
	global_load_dwordx4 v[84:87], v[188:189], off
	s_waitcnt lgkmcnt(5)
	v_mfma_f32_32x32x16_bf16 v[172:187], v[114:117], v[52:55], v[172:187]
	ds_read_b128 v[114:117], v128 offset:13344
	v_add_f32_e32 v108, v33, v108
	v_cvt_pk_bf16_f32 v154, v32, v33
	v_exp_f32_e32 v35, v35
	v_add_f32_e32 v108, v34, v108
	v_lshl_add_u64 v[190:191], v[94:95], 1, s[36:37]
	global_load_dwordx4 v[72:75], v[190:191], off
	s_waitcnt lgkmcnt(5)
	v_mfma_f32_32x32x16_bf16 v[172:187], v[118:121], v[56:59], v[172:187]
	ds_read_b128 v[118:121], v128 offset:13376
	v_exp_f32_e32 v36, v36
	v_add_f32_e32 v108, v35, v108
	v_cvt_pk_bf16_f32 v155, v34, v35
	v_exp_f32_e32 v37, v37
	v_lshl_add_u64 v[192:193], v[96:97], 1, s[36:37]
	global_load_dwordx4 v[76:79], v[192:193], off
	s_waitcnt lgkmcnt(5)
	v_mfma_f32_32x32x16_bf16 v[172:187], v[122:125], v[60:63], v[172:187]
	ds_read_b128 v[122:125], v128 offset:13408
	v_add_f32_e32 v108, v36, v108
	v_exp_f32_e32 v38, v38
	v_add_f32_e32 v108, v37, v108
	v_cvt_pk_bf16_f32 v156, v36, v37
	v_lshl_add_u64 v[188:189], v[98:99], 0, s[30:31]
	global_load_dwordx4 v[80:83], v[188:189], off
	s_add_u32 s30, s30, s39
	s_waitcnt lgkmcnt(5)
	v_mfma_f32_32x32x16_bf16 v[172:187], v[130:133], v[64:67], v[172:187]
	ds_read_b128 v[130:133], v128 offset:13440
	v_exp_f32_e32 v39, v39
	v_add_f32_e32 v108, v38, v108
	v_exp_f32_e32 v40, v40
	v_add_f32_e32 v108, v39, v108
	v_lshl_add_u64 v[190:191], v[98:99], 0, s[30:31]
	global_load_dwordx4 v[88:91], v[190:191], off
	s_mul_i32 s35, s28, 0xac00
	s_waitcnt lgkmcnt(5)
	v_mfma_f32_32x32x16_bf16 v[172:187], v[134:137], v[68:71], v[172:187]
	ds_read_b128 v[134:137], v128 offset:13472
	v_cvt_pk_bf16_f32 v157, v38, v39
	v_exp_f32_e32 v41, v41
	v_add_f32_e32 v108, v40, v108
	v_exp_f32_e32 v42, v42
	s_waitcnt lgkmcnt(14)
	v_mfma_f32_32x32x16_bf16 v[0:15], v[138:141], v[162:165], v[0:15]
	ds_read_b128 v[138:141], v170 offset:26624
	v_add_f32_e32 v108, v41, v108
	v_cvt_pk_bf16_f32 v158, v40, v41
	v_exp_f32_e32 v43, v43
	v_add_f32_e32 v108, v42, v108
	s_waitcnt lgkmcnt(14)
	v_mfma_f32_32x32x16_bf16 v[16:31], v[146:149], v[162:165], v[16:31]
	ds_read_b128 v[146:149], v170 offset:35328
	v_exp_f32_e32 v44, v44
	v_add_f32_e32 v108, v43, v108
	v_cvt_pk_bf16_f32 v159, v42, v43
	v_exp_f32_e32 v45, v45
	s_waitcnt lgkmcnt(14)
	v_mfma_f32_32x32x16_bf16 v[0:15], v[142:145], v[166:169], v[0:15]
	ds_read_b128 v[142:145], v170 offset:26656
	v_add_f32_e32 v108, v44, v108
	v_exp_f32_e32 v46, v46
	v_add_f32_e32 v108, v45, v108
	v_cvt_pk_bf16_f32 v160, v44, v45
	s_waitcnt lgkmcnt(14)
	v_mfma_f32_32x32x16_bf16 v[16:31], v[150:153], v[166:169], v[16:31]
	ds_read_b128 v[150:153], v170 offset:35360
	v_exp_f32_e32 v47, v47
	v_add_f32_e32 v108, v46, v108
	v_add_f32_e32 v108, v47, v108
	v_cvt_pk_bf16_f32 v161, v46, v47
	s_waitcnt lgkmcnt(9)
	v_mfma_f32_32x32x16_bf16 v[32:47], v[110:113], v[48:51], 0
	ds_read_b128 v[110:113], v128 offset:19968
	v_exp_f32_e32 v172, v172
	v_exp_f32_e32 v173, v173
	v_add_f32_e32 v108, v172, v108
	v_exp_f32_e32 v174, v174
	s_waitcnt lgkmcnt(9)
	v_mfma_f32_32x32x16_bf16 v[32:47], v[114:117], v[52:55], v[32:47]
	ds_read_b128 v[114:117], v128 offset:20000
	v_add_f32_e32 v108, v173, v108
	v_cvt_pk_bf16_f32 v162, v172, v173
	v_exp_f32_e32 v175, v175
	v_add_f32_e32 v108, v174, v108
	s_waitcnt lgkmcnt(9)
; #define KLOAD(kf_, base)                                                                       \
;   { _Pragma("unroll") for (int ks = 0; ks < NKS; ks++) kf_[ks] = *(const bf16x8*)((base) + kfo + ks * 32); }
; #define VLOAD(vf_, base)                                                                       \
;   { _Pragma("unroll") for (int q = 0; q < 4; q++) vf_[q] = *(const bf16x8*)((base) + vfo + (q >> 1) * 32 * VROW + (q & 1) * 32); }
; #define QKM(dst, kf_)                                                                          \
;   {                                                                                            \
;     _Pragma("unroll") for (int i = 0; i < 16; i++) dst[i] = 0.f;                               \
;     _Pragma("unroll") for (int ks = 0; ks < NKS; ks++) dst = MFMA(kf_[ks], qf[ks], dst);       \
;   }
; #define SB() __builtin_amdgcn_sched_barrier(0)
; template <int DK>
; DI void attn_core(const bf16x8 (&qf)[DK / 16], const short* Kg, const short* VTg, size_t ldvt, int ntiles, char* smem,
;                   f32x16 (&O)[2], float& lsum) {
;     ...
;     QKM(Sc, kf);
;     PVM(vf, pa, pb);
;     SB();
;     KLOAD(kf, cur + 96 * KROW);
;     VLOAD(vf, cur + 64);
;     SB();
;     SOFTMAX(Sc, pa, pb, l0);
;     SB();
;     QKM(Sn, kf);
;     PVM(vf, qa, qb);
;     SB();
;     KLOAD(kf, nxt);
;     VLOAD(vf, cur + 128);
;     SB();
;     SOFTMAX(Sn, qa, qb, l0);
;     SB();
;     QKM(Sc, kf);
;     PVM(vf, pa, pb);
;     SB();
;     VLOAD(vf, cur + 192);
;     PVM(vf, qa, qb);
;     ASTORE(sw);
	v_mfma_f32_32x32x16_bf16 v[32:47], v[118:121], v[56:59], v[32:47]
	ds_read_b128 v[118:121], v128 offset:20032
	v_exp_f32_e32 v176, v176
	v_add_f32_e32 v108, v175, v108
	v_cvt_pk_bf16_f32 v163, v174, v175
	v_exp_f32_e32 v177, v177
	s_waitcnt lgkmcnt(9)
	v_mfma_f32_32x32x16_bf16 v[32:47], v[122:125], v[60:63], v[32:47]
	ds_read_b128 v[122:125], v128 offset:20064
	v_add_f32_e32 v108, v176, v108
	v_exp_f32_e32 v178, v178
	v_add_f32_e32 v108, v177, v108
	v_cvt_pk_bf16_f32 v164, v176, v177
	s_waitcnt lgkmcnt(9)
	v_mfma_f32_32x32x16_bf16 v[32:47], v[130:133], v[64:67], v[32:47]
	ds_read_b128 v[130:133], v128 offset:20096
	v_exp_f32_e32 v179, v179
	v_add_f32_e32 v108, v178, v108
	v_exp_f32_e32 v180, v180
	v_add_f32_e32 v108, v179, v108
	s_waitcnt lgkmcnt(9)
	v_mfma_f32_32x32x16_bf16 v[32:47], v[134:137], v[68:71], v[32:47]
	ds_read_b128 v[134:137], v128 offset:20128
	v_cvt_pk_bf16_f32 v165, v178, v179
	v_exp_f32_e32 v181, v181
	v_add_f32_e32 v108, v180, v108
	v_exp_f32_e32 v182, v182
	s_waitcnt lgkmcnt(9)
	v_mfma_f32_32x32x16_bf16 v[0:15], v[138:141], v[154:157], v[0:15]
	ds_read_b128 v[138:141], v170 offset:26688
	v_add_f32_e32 v108, v181, v108
	v_cvt_pk_bf16_f32 v166, v180, v181
	v_exp_f32_e32 v183, v183
	v_add_f32_e32 v108, v182, v108
	s_waitcnt lgkmcnt(9)
	v_mfma_f32_32x32x16_bf16 v[16:31], v[146:149], v[154:157], v[16:31]
	ds_read_b128 v[146:149], v170 offset:35392
	v_exp_f32_e32 v184, v184
	v_add_f32_e32 v108, v183, v108
	v_cvt_pk_bf16_f32 v167, v182, v183
	v_exp_f32_e32 v185, v185
	s_waitcnt lgkmcnt(9)
	v_mfma_f32_32x32x16_bf16 v[0:15], v[142:145], v[158:161], v[0:15]
	ds_read_b128 v[142:145], v170 offset:26720
	v_add_f32_e32 v108, v184, v108
	v_exp_f32_e32 v186, v186
	v_add_f32_e32 v108, v185, v108
	v_cvt_pk_bf16_f32 v168, v184, v185
	s_waitcnt lgkmcnt(9)
	v_mfma_f32_32x32x16_bf16 v[16:31], v[150:153], v[158:161], v[16:31]
	ds_read_b128 v[150:153], v170 offset:35424
	v_exp_f32_e32 v187, v187
	v_add_f32_e32 v108, v186, v108
	v_add_f32_e32 v108, v187, v108
	v_cvt_pk_bf16_f32 v169, v186, v187
	s_waitcnt lgkmcnt(9)
	v_mfma_f32_32x32x16_bf16 v[172:187], v[110:113], v[48:51], 0
	ds_read_b128 v[110:113], v109 offset:0
	v_exp_f32_e32 v32, v32
	v_exp_f32_e32 v33, v33
	v_add_f32_e32 v108, v32, v108
	v_exp_f32_e32 v34, v34
	s_waitcnt lgkmcnt(9)
	v_mfma_f32_32x32x16_bf16 v[172:187], v[114:117], v[52:55], v[172:187]
	ds_read_b128 v[114:117], v109 offset:32
	v_add_f32_e32 v108, v33, v108
	v_cvt_pk_bf16_f32 v154, v32, v33
	v_exp_f32_e32 v35, v35
	v_add_f32_e32 v108, v34, v108
	s_waitcnt lgkmcnt(9)
	v_mfma_f32_32x32x16_bf16 v[172:187], v[118:121], v[56:59], v[172:187]
	ds_read_b128 v[118:121], v109 offset:64
	v_exp_f32_e32 v36, v36
	v_add_f32_e32 v108, v35, v108
	v_cvt_pk_bf16_f32 v155, v34, v35
	v_exp_f32_e32 v37, v37
	s_waitcnt lgkmcnt(9)
	v_mfma_f32_32x32x16_bf16 v[172:187], v[122:125], v[60:63], v[172:187]
	ds_read_b128 v[122:125], v109 offset:96
	v_add_f32_e32 v108, v36, v108
	v_exp_f32_e32 v38, v38
	v_add_f32_e32 v108, v37, v108
	v_cvt_pk_bf16_f32 v156, v36, v37
	s_waitcnt lgkmcnt(9)
	v_mfma_f32_32x32x16_bf16 v[172:187], v[130:133], v[64:67], v[172:187]
	ds_read_b128 v[130:133], v109 offset:128
	v_exp_f32_e32 v39, v39
	v_add_f32_e32 v108, v38, v108
	v_exp_f32_e32 v40, v40
	v_add_f32_e32 v108, v39, v108
	s_waitcnt lgkmcnt(9)
	v_mfma_f32_32x32x16_bf16 v[172:187], v[134:137], v[68:71], v[172:187]
	ds_read_b128 v[134:137], v109 offset:160
	v_cvt_pk_bf16_f32 v157, v38, v39
	v_exp_f32_e32 v41, v41
	v_add_f32_e32 v108, v40, v108
	v_exp_f32_e32 v42, v42
	s_waitcnt lgkmcnt(9)
	v_mfma_f32_32x32x16_bf16 v[0:15], v[138:141], v[162:165], v[0:15]
	ds_read_b128 v[138:141], v170 offset:26752
	v_add_f32_e32 v108, v41, v108
	v_cvt_pk_bf16_f32 v158, v40, v41
	v_exp_f32_e32 v43, v43
	v_add_f32_e32 v108, v42, v108
	s_waitcnt lgkmcnt(9)
	v_mfma_f32_32x32x16_bf16 v[16:31], v[146:149], v[162:165], v[16:31]
	ds_read_b128 v[146:149], v170 offset:35456
	v_exp_f32_e32 v44, v44
	v_add_f32_e32 v108, v43, v108
	v_cvt_pk_bf16_f32 v159, v42, v43
	v_exp_f32_e32 v45, v45
	s_waitcnt lgkmcnt(9)
	v_mfma_f32_32x32x16_bf16 v[0:15], v[142:145], v[166:169], v[0:15]
	ds_read_b128 v[142:145], v170 offset:26784
	v_add_f32_e32 v108, v44, v108
	v_exp_f32_e32 v46, v46
	v_add_f32_e32 v108, v45, v108
	v_cvt_pk_bf16_f32 v160, v44, v45
	s_waitcnt lgkmcnt(9)
	v_mfma_f32_32x32x16_bf16 v[16:31], v[150:153], v[166:169], v[16:31]
	ds_read_b128 v[150:153], v170 offset:35488
	v_exp_f32_e32 v47, v47
	v_add_f32_e32 v108, v46, v108
	v_add_f32_e32 v108, v47, v108
	v_cvt_pk_bf16_f32 v161, v46, v47
	s_waitcnt lgkmcnt(3)
	v_mfma_f32_32x32x16_bf16 v[0:15], v[138:141], v[154:157], v[0:15]
	ds_read_b128 v[138:141], v170 offset:26816
	v_exp_f32_e32 v172, v172
	v_exp_f32_e32 v173, v173
	v_add_f32_e32 v108, v172, v108
	v_exp_f32_e32 v174, v174
	v_add_u32_e32 v188, s35, v104
	s_waitcnt vmcnt(4)
	ds_write_b128 v188, v[84:87]
	s_waitcnt lgkmcnt(4)
	v_mfma_f32_32x32x16_bf16 v[16:31], v[146:149], v[154:157], v[16:31]
	ds_read_b128 v[146:149], v170 offset:35520
	v_add_f32_e32 v108, v173, v108
	v_cvt_pk_bf16_f32 v162, v172, v173
	v_exp_f32_e32 v175, v175
	v_add_f32_e32 v108, v174, v108
	v_add_u32_e32 v189, s35, v105
	s_waitcnt vmcnt(3)
	ds_write_b128 v189, v[72:75]
	s_waitcnt lgkmcnt(5)
	v_mfma_f32_32x32x16_bf16 v[0:15], v[142:145], v[158:161], v[0:15]
	ds_read_b128 v[142:145], v170 offset:26848
	v_exp_f32_e32 v176, v176
	v_add_f32_e32 v108, v175, v108
	v_cvt_pk_bf16_f32 v163, v174, v175
	v_exp_f32_e32 v177, v177
	v_add_u32_e32 v190, s35, v106
	s_waitcnt vmcnt(2)
	ds_write_b128 v190, v[76:79]
	s_waitcnt lgkmcnt(6)
; template <int DK>
; DI void attn_core(const bf16x8 (&qf)[DK / 16], const short* Kg, const short* VTg, size_t ldvt, int ntiles, char* smem,
;                   f32x16 (&O)[2], float& lsum) {
;     ...
;     const int tn = t + 2 < ntiles ? t + 2 : ntiles - 1;
;     AGLOAD(tn);
;     const char* cur = smem + sc * ST;
;     const char* nxt = smem + sn * ST;
;     ...
;     ASTORE(sw);
;     __syncthreads();
;     const int tmp = sc; sc = sn; sn = sw; sw = tmp;
	v_mfma_f32_32x32x16_bf16 v[16:31], v[150:153], v[158:161], v[16:31]
	ds_read_b128 v[150:153], v170 offset:35552
	v_add_f32_e32 v108, v176, v108
	v_exp_f32_e32 v178, v178
	v_add_f32_e32 v108, v177, v108
	v_cvt_pk_bf16_f32 v164, v176, v177
	v_add_u32_e32 v191, s35, v100
	s_waitcnt vmcnt(1)
	ds_write_b128 v191, v[80:83] offset:26624
	s_waitcnt lgkmcnt(14)
	v_mfma_f32_32x32x16_bf16 v[32:47], v[110:113], v[48:51], 0
	ds_read_b128 v[110:113], v109 offset:6656
	v_exp_f32_e32 v179, v179
	v_add_f32_e32 v108, v178, v108
	v_exp_f32_e32 v180, v180
	v_add_f32_e32 v108, v179, v108
	s_waitcnt vmcnt(0)
	ds_write_b128 v191, v[88:91] offset:35328
	s_waitcnt lgkmcnt(14)
	v_mfma_f32_32x32x16_bf16 v[32:47], v[114:117], v[52:55], v[32:47]
	ds_read_b128 v[114:117], v109 offset:6688
	v_cvt_pk_bf16_f32 v165, v178, v179
	v_exp_f32_e32 v181, v181
	v_add_f32_e32 v108, v180, v108
	v_exp_f32_e32 v182, v182
	s_waitcnt lgkmcnt(14)
	v_mfma_f32_32x32x16_bf16 v[32:47], v[118:121], v[56:59], v[32:47]
	ds_read_b128 v[118:121], v109 offset:6720
	v_add_f32_e32 v108, v181, v108
	v_cvt_pk_bf16_f32 v166, v180, v181
	v_exp_f32_e32 v183, v183
	v_add_f32_e32 v108, v182, v108
	s_waitcnt lgkmcnt(14)
	v_mfma_f32_32x32x16_bf16 v[32:47], v[122:125], v[60:63], v[32:47]
	ds_read_b128 v[122:125], v109 offset:6752
	v_exp_f32_e32 v184, v184
	v_add_f32_e32 v108, v183, v108
	v_cvt_pk_bf16_f32 v167, v182, v183
	v_exp_f32_e32 v185, v185
	s_waitcnt lgkmcnt(14)
	v_mfma_f32_32x32x16_bf16 v[32:47], v[130:133], v[64:67], v[32:47]
	ds_read_b128 v[130:133], v109 offset:6784
	v_add_f32_e32 v108, v184, v108
	v_exp_f32_e32 v186, v186
	v_add_f32_e32 v108, v185, v108
	v_cvt_pk_bf16_f32 v168, v184, v185
	s_waitcnt lgkmcnt(14)
	v_mfma_f32_32x32x16_bf16 v[32:47], v[134:137], v[68:71], v[32:47]
	ds_read_b128 v[134:137], v109 offset:6816
	v_exp_f32_e32 v187, v187
	v_add_f32_e32 v108, v186, v108
	v_add_f32_e32 v108, v187, v108
	v_cvt_pk_bf16_f32 v169, v186, v187
	s_add_i32 s23, s23, 1
	s_mov_b32 s30, s15
	s_mov_b32 s15, s34
	s_mov_b32 s34, s28
	s_mov_b32 s28, s30
	s_add_i32 s35, s23, 2
	s_min_u32 s35, s35, s14
	s_mul_i32 s36, s35, 0x6000
	s_mul_hi_u32 s37, s35, 0x6000
	s_add_u32 s36, s8, s36
	s_addc_u32 s37, s9, s37
	s_lshl_b32 s30, s35, 8
	s_mul_i32 s35, s15, 0xac00
	v_add_u32_e32 v128, s35, v107
	v_add_u32_e32 v170, s35, v101
	s_mul_i32 s35, s34, 0xac00
	v_add_u32_e32 v109, s35, v107
	s_cmp_lg_u32 s29, s23
	s_waitcnt lgkmcnt(5)
	s_barrier
	s_cbranch_scc1 .Lmla_sample_loop
	s_waitcnt lgkmcnt(0)
	s_barrier
; DI int my_tid() { int t = threadIdx.x; asm volatile("" : "+v"(t)); return t; }
; DI float bf_lo(unsigned u) { return __uint_as_float(u << 16); }
; DI float bf_hi(unsigned u) { return __uint_as_float(u & 0xffff0000u); }
; template <int DK>
; DI void attn_core(const bf16x8 (&qf)[DK / 16], const short* Kg, const short* VTg, size_t ldvt, int ntiles, char* smem,
;                   f32x16 (&O)[2], float& lsum) {
;     ...
;     PVM(vf, qa, qb);
; DI void attn_store(const f32x16 (&O)[2], float lsum, int tok, int col0, const short* gate, short* o, char* smem) {
;   const int tid = my_tid(), lane = tid & 63, w = tid >> 6, r = lane & 31, h = lane >> 5;
;   float l = lsum + __shfl_xor(lsum, 32);
;   float inv = __builtin_amdgcn_rcpf(l);
;   float* pw = (float*)(smem + w * (32 * 68 * 4));
;   const int tokw = tok - r;
;   const int ch = lane & 7;
;   u32x4 gpre[4];
; #pragma unroll
;   for (int j = 0; j < 4; j++) gpre[j] = *(const u32x4*)(gate + (size_t)(tokw + j * 8 + (lane >> 3)) * 1024 + col0 + ch * 8);
; #pragma unroll
;   for (int dt = 0; dt < 2; dt++)
; #pragma unroll
;     for (int q = 0; q < 4; q++) {
;       f32x4 t = {O[dt][q * 4 + 0] * inv, O[dt][q * 4 + 1] * inv, O[dt][q * 4 + 2] * inv, O[dt][q * 4 + 3] * inv};
;       *(f32x4*)(pw + r * 68 + dt * 32 + 8 * q + 4 * h) = t;
;     }
;   asm volatile("s_waitcnt lgkmcnt(0)" ::: "memory");
; #pragma unroll
;   for (int j = 0; j < 4; j++) {
;     const int row = j * 8 + (lane >> 3);
;     const size_t g = (size_t)(tokw + row) * 1024 + col0 + ch * 8;
;     const u32x4 gv = gpre[j];
;     const f32x4 a = *(const f32x4*)(pw + row * 68 + ch * 8), c = *(const f32x4*)(pw + row * 68 + ch * 8 + 4);
;     u32x4 ov;
;     ov[0] = pack_bf16(a[0] * bf_lo(gv[0]), a[1] * bf_hi(gv[0]));
;     ov[1] = pack_bf16(a[2] * bf_lo(gv[1]), a[3] * bf_hi(gv[1]));
;     ov[2] = pack_bf16(c[0] * bf_lo(gv[2]), c[1] * bf_hi(gv[2]));
;     ov[3] = pack_bf16(c[2] * bf_lo(gv[3]), c[3] * bf_hi(gv[3]));
;     __builtin_nontemporal_store(ov, (u32x4*)(o + g));
;   }
;   __syncthreads();
; }
	v_mfma_f32_32x32x16_bf16 v[0:15], v[138:141], v[162:165], v[0:15]
	v_mfma_f32_32x32x16_bf16 v[16:31], v[146:149], v[162:165], v[16:31]
	v_mfma_f32_32x32x16_bf16 v[0:15], v[142:145], v[166:169], v[0:15]
	v_mfma_f32_32x32x16_bf16 v[16:31], v[150:153], v[166:169], v[16:31]
	s_nop 10
	ds_bpermute_b32 v33, v103, v108
	s_lshl_b32 s8, s16, 6
	v_mov_b32_e32 v57, v196
	s_ashr_i32 s9, s8, 31
	v_lshrrev_b32_e32 v32, 6, v57
	v_and_b32_e32 v58, 31, v57
	s_waitcnt lgkmcnt(0)
	v_add_f32_e32 v56, v108, v33
	v_mul_lo_u32 v59, v32, s38
	v_sub_u32_e32 v32, v102, v58
	v_bfe_u32 v60, v57, 3, 3
	s_lshl_b64 s[8:9], s[8:9], 1
	v_lshlrev_b32_e32 v33, 3, v57
	v_add_u32_e32 v32, v60, v32
	s_add_u32 s14, s18, s8
	v_and_b32_e32 v61, 56, v33
	s_addc_u32 s15, s19, s9
	v_lshlrev_b32_e32 v128, 1, v61
	v_ashrrev_i32_e32 v33, 31, v32
	v_lshl_add_u64 v[34:35], s[14:15], 0, v[128:129]
	v_lshlrev_b64 v[54:55], 11, v[32:33]
	v_lshl_add_u64 v[36:37], v[34:35], 0, v[54:55]
	global_load_dwordx4 v[44:47], v[36:37], off
	v_add_u32_e32 v36, 8, v32
	v_ashrrev_i32_e32 v37, 31, v36
	v_lshlrev_b64 v[52:53], 11, v[36:37]
	v_lshl_add_u64 v[36:37], v[34:35], 0, v[52:53]
	global_load_dwordx4 v[40:43], v[36:37], off
	v_add_u32_e32 v36, 16, v32
	v_ashrrev_i32_e32 v37, 31, v36
	v_lshlrev_b64 v[50:51], 11, v[36:37]
	v_lshl_add_u64 v[36:37], v[34:35], 0, v[50:51]
	global_load_dwordx4 v[36:39], v[36:37], off
	v_add_u32_e32 v32, 24, v32
	v_ashrrev_i32_e32 v33, 31, v32
	v_lshlrev_b64 v[48:49], 11, v[32:33]
	v_lshl_add_u64 v[32:33], v[34:35], 0, v[48:49]
	global_load_dwordx4 v[32:35], v[32:33], off
	v_rcp_f32_e32 v56, v56
	v_lshrrev_b32_e32 v57, 1, v57
	v_mul_u32_u24_e32 v58, 0x110, v58
	v_and_b32_e32 v57, 16, v57
	v_add3_u32 v57, v59, v58, v57
	v_pk_mul_f32 v[0:1], v[0:1], v[56:57] op_sel_hi:[1,0]
	v_pk_mul_f32 v[2:3], v[2:3], v[56:57] op_sel_hi:[1,0]
	ds_write_b128 v57, v[0:3]
	v_pk_mul_f32 v[0:1], v[4:5], v[56:57] op_sel_hi:[1,0]
	v_pk_mul_f32 v[2:3], v[6:7], v[56:57] op_sel_hi:[1,0]
	ds_write_b128 v57, v[0:3] offset:32
	v_pk_mul_f32 v[0:1], v[8:9], v[56:57] op_sel_hi:[1,0]
	v_pk_mul_f32 v[2:3], v[10:11], v[56:57] op_sel_hi:[1,0]
	ds_write_b128 v57, v[0:3] offset:64
	v_pk_mul_f32 v[0:1], v[12:13], v[56:57] op_sel_hi:[1,0]
	v_pk_mul_f32 v[2:3], v[14:15], v[56:57] op_sel_hi:[1,0]
	ds_write_b128 v57, v[0:3] offset:96
	v_pk_mul_f32 v[0:1], v[16:17], v[56:57] op_sel_hi:[1,0]
	v_pk_mul_f32 v[2:3], v[18:19], v[56:57] op_sel_hi:[1,0]
	ds_write_b128 v57, v[0:3] offset:128
	v_pk_mul_f32 v[0:1], v[20:21], v[56:57] op_sel_hi:[1,0]
	v_pk_mul_f32 v[2:3], v[22:23], v[56:57] op_sel_hi:[1,0]
	ds_write_b128 v57, v[0:3] offset:160
	v_pk_mul_f32 v[0:1], v[24:25], v[56:57] op_sel_hi:[1,0]
	v_pk_mul_f32 v[2:3], v[26:27], v[56:57] op_sel_hi:[1,0]
	ds_write_b128 v57, v[0:3] offset:192
	v_pk_mul_f32 v[0:1], v[28:29], v[56:57] op_sel_hi:[1,0]
	v_pk_mul_f32 v[2:3], v[30:31], v[56:57] op_sel_hi:[1,0]
	ds_write_b128 v57, v[0:3] offset:224
	v_lshl_or_b32 v2, v61, 2, v59
	s_movk_i32 s36, 0x110
	s_waitcnt lgkmcnt(0)
	v_mad_u32_u24 v12, v60, s36, v2
	ds_read_b128 v[2:5], v12
	ds_read_b128 v[6:9], v12 offset:16
	s_add_u32 s8, s20, s8
	s_addc_u32 s9, s21, s9
	v_lshl_add_u64 v[0:1], s[8:9], 0, v[128:129]
	v_readlane_b32 s8, v226, 12
	s_add_i32 s22, s22, s8
	s_cmpk_gt_i32 s22, 0x17f
	s_waitcnt vmcnt(3)
	v_lshlrev_b32_e32 v10, 16, v44
	v_and_b32_e32 v11, 0xffff0000, v44
	s_waitcnt lgkmcnt(1)
	v_pk_mul_f32 v[2:3], v[2:3], v[10:11]
	v_lshlrev_b32_e32 v10, 16, v45
	v_and_b32_e32 v11, 0xffff0000, v45
	v_pk_mul_f32 v[4:5], v[4:5], v[10:11]
	v_cvt_pk_bf16_f32 v2, v2, v3
	v_cvt_pk_bf16_f32 v3, v4, v5
	v_lshlrev_b32_e32 v4, 16, v46
	v_and_b32_e32 v5, 0xffff0000, v46
	s_waitcnt lgkmcnt(0)
	v_pk_mul_f32 v[4:5], v[6:7], v[4:5]
	v_lshlrev_b32_e32 v6, 16, v47
	v_and_b32_e32 v7, 0xffff0000, v47
	v_pk_mul_f32 v[6:7], v[8:9], v[6:7]
	v_cvt_pk_bf16_f32 v4, v4, v5
	v_cvt_pk_bf16_f32 v5, v6, v7
	v_lshl_add_u64 v[6:7], v[0:1], 0, v[54:55]
	global_store_dwordx4 v[6:7], v[2:5], off nt
	ds_read_b128 v[2:5], v12 offset:2176
	ds_read_b128 v[6:9], v12 offset:2192
	s_waitcnt vmcnt(3)
	v_lshlrev_b32_e32 v10, 16, v40
	v_and_b32_e32 v11, 0xffff0000, v40
	s_waitcnt lgkmcnt(1)
	v_pk_mul_f32 v[2:3], v[2:3], v[10:11]
	v_lshlrev_b32_e32 v10, 16, v41
	v_and_b32_e32 v11, 0xffff0000, v41
	v_pk_mul_f32 v[4:5], v[4:5], v[10:11]
	v_cvt_pk_bf16_f32 v2, v2, v3
	v_cvt_pk_bf16_f32 v3, v4, v5
	v_lshlrev_b32_e32 v4, 16, v42
	v_and_b32_e32 v5, 0xffff0000, v42
	s_waitcnt lgkmcnt(0)
	v_pk_mul_f32 v[4:5], v[6:7], v[4:5]
	v_lshlrev_b32_e32 v6, 16, v43
	v_and_b32_e32 v7, 0xffff0000, v43
	v_pk_mul_f32 v[6:7], v[8:9], v[6:7]
	v_cvt_pk_bf16_f32 v4, v4, v5
	v_cvt_pk_bf16_f32 v5, v6, v7
	v_lshl_add_u64 v[6:7], v[0:1], 0, v[52:53]
	global_store_dwordx4 v[6:7], v[2:5], off nt
	ds_read_b128 v[2:5], v12 offset:4352
	ds_read_b128 v[6:9], v12 offset:4368
	s_waitcnt vmcnt(3)
	v_lshlrev_b32_e32 v10, 16, v36
	v_and_b32_e32 v11, 0xffff0000, v36
	s_waitcnt lgkmcnt(1)
	v_pk_mul_f32 v[2:3], v[2:3], v[10:11]
	v_lshlrev_b32_e32 v10, 16, v37
	v_and_b32_e32 v11, 0xffff0000, v37
	v_pk_mul_f32 v[4:5], v[4:5], v[10:11]
	v_cvt_pk_bf16_f32 v2, v2, v3
	v_cvt_pk_bf16_f32 v3, v4, v5
	v_lshlrev_b32_e32 v4, 16, v38
	v_and_b32_e32 v5, 0xffff0000, v38
	s_waitcnt lgkmcnt(0)
	v_pk_mul_f32 v[4:5], v[6:7], v[4:5]
	v_lshlrev_b32_e32 v6, 16, v39
	v_and_b32_e32 v7, 0xffff0000, v39
	v_pk_mul_f32 v[6:7], v[8:9], v[6:7]
	v_cvt_pk_bf16_f32 v4, v4, v5
	v_cvt_pk_bf16_f32 v5, v6, v7
	v_lshl_add_u64 v[6:7], v[0:1], 0, v[50:51]
	global_store_dwordx4 v[6:7], v[2:5], off nt
	ds_read_b128 v[2:5], v12 offset:6528
	ds_read_b128 v[6:9], v12 offset:6544
	s_waitcnt vmcnt(3)
	v_lshlrev_b32_e32 v10, 16, v32
	v_and_b32_e32 v11, 0xffff0000, v32
	v_lshl_add_u64 v[0:1], v[0:1], 0, v[48:49]
	s_waitcnt lgkmcnt(1)
	v_pk_mul_f32 v[2:3], v[2:3], v[10:11]
	v_lshlrev_b32_e32 v10, 16, v33
	v_and_b32_e32 v11, 0xffff0000, v33
	v_pk_mul_f32 v[4:5], v[4:5], v[10:11]
	v_cvt_pk_bf16_f32 v2, v2, v3
	v_cvt_pk_bf16_f32 v3, v4, v5
	v_lshlrev_b32_e32 v4, 16, v34
	v_and_b32_e32 v5, 0xffff0000, v34
	s_waitcnt lgkmcnt(0)
	v_pk_mul_f32 v[4:5], v[6:7], v[4:5]
	v_lshlrev_b32_e32 v6, 16, v35
	v_and_b32_e32 v7, 0xffff0000, v35
	v_pk_mul_f32 v[6:7], v[8:9], v[6:7]
	v_cvt_pk_bf16_f32 v4, v4, v5
	v_cvt_pk_bf16_f32 v5, v6, v7
	global_store_dwordx4 v[0:1], v[2:5], off nt
	s_barrier
	s_cbranch_scc0 .LBB0_170
